# v079 + GEMM loops: loop-carried scalar updates, exit test and next iteration's scalar address selection moved into the middle of the last MFMA block (off the post-barrier load path)
# baseline (speedup 1.0000x reference)
; #define PG8_STAGE(bufoff, gbase, voff) do { _Pragma("unroll") for (int _i = 0; _i < 2; ++_i) \
;         __builtin_amdgcn_global_load_lds((const gunsigned*)((const gchar*)(gbase) + (voff)[_i]), (LAS unsigned*)(lds + (bufoff) + ldsw + _i * 8192), 16, 0, 0); } while (0)
; #define PG8_LDA(dst, b, h) do { _Pragma("unroll") for (int m = 0; m < 4; ++m) _Pragma("unroll") for (int k = 0; k < 2; ++k) dst[m][k] = *(const LAS bf16x8*)(lds + PG8_SA(b, h) + aoff + m * 2048 + k * 1024); } while (0)
; #define PG8_LDB(dst, b, h) do { _Pragma("unroll") for (int n = 0; n < 2; ++n) _Pragma("unroll") for (int k = 0; k < 2; ++k) dst[n][k] = *(const LAS bf16x8*)(lds + PG8_SB(b, h) + boff + n * 2048 + k * 1024); } while (0)
; #define PG8_MMA(ai, bj, At, Bt) do { __builtin_amdgcn_s_setprio(1); _Pragma("unroll") for (int m = 0; m < 4; ++m) _Pragma("unroll") for (int n = 0; n < 2; ++n) _Pragma("unroll") for (int k = 0; k < 2; ++k) \
;         acc[ai][bj][m][n] = __builtin_amdgcn_mfma_f32_16x16x32_bf16(Bt[n][k], At[m][k], acc[ai][bj][m][n], 0, 0, 0); __builtin_amdgcn_s_setprio(0); } while (0)
; #define PG8_WAIT_V(n) asm volatile("s_waitcnt vmcnt(" #n ")" ::: "memory")
; #define PG8_WAIT_L(n) asm volatile("s_waitcnt lgkmcnt(" #n ")" ::: "memory")
; #define PG8_BAR __builtin_amdgcn_s_barrier()
; #define PG8_SCHED __builtin_amdgcn_sched_barrier(0)
; template <class Epi, class Sched>
; __device__ __forceinline__ void gemm_phase(LAS unsigned char* lds, const int tid, const Gemm g, const Sched& S, const Epi& E) {
;     ...
;         for (int t = 0; t < nt; t += 2) {
;             const bool last = (t == nt - 2);
;             const gchar* a1 = cA + (size_t)(t + 1) * kstep;
;             const gchar* a2 = last ? nA : cA + (size_t)(t + 2) * kstep; const gchar* b2 = last ? nB : cB + (size_t)(t + 2) * kstep;
;             const gchar* a3 = a2 + kstep; const gchar* b3 = b2 + kstep;
;             PG8_LDB(B0, 0, 0); PG8_LDB(B1, 0, 1); PG8_SCHED; PG8_LDA(At, 0, 0); PG8_STAGE(PG8_SA(1, 1), a1 + hstep, voffA);
;             PG8_WAIT_V(8); PG8_WAIT_L(0); PG8_BAR; PG8_MMA(0, 0, At, B0); PG8_MMA(0, 1, At, B1); PG8_BAR; PG8_SCHED;
;             PG8_LDA(At, 0, 1); PG8_STAGE(PG8_SB(0, 0), b2, voffB); PG8_STAGE(PG8_SB(0, 1), b2 + hstep, voffB); PG8_STAGE(PG8_SA(0, 0), a2, voffA);
;             PG8_WAIT_V(8); PG8_WAIT_L(0); PG8_BAR; PG8_MMA(1, 0, At, B0); PG8_MMA(1, 1, At, B1); PG8_BAR; PG8_SCHED;
.LBB0_319:
	s_add_u32 vcc_lo, s10, 0x100
	s_addc_u32 vcc_hi, s11, 0
	s_cmp_eq_u32 s29, 40
	s_cselect_b32 s75, s21, vcc_hi
	s_cselect_b32 s74, s20, vcc_lo
	s_cselect_b32 s73, s1, s93
	s_cselect_b32 s72, s0, s31
.Lrot_319:
	s_add_i32 s39, 0, 0x10000
	s_add_i32 s30, 0, 0x14000
	v_add_u32_e32 v142, s39, v174
	v_add_u32_e32 v168, s30, v174
	ds_read_b128 v[130:133], v142
	ds_read_b128 v[134:137], v142 offset:1024
	ds_read_b128 v[138:141], v142 offset:2048
	ds_read_b128 v[142:145], v142 offset:3072
	ds_read_b128 v[146:149], v168
	ds_read_b128 v[150:153], v168 offset:1024
	ds_read_b128 v[164:167], v168 offset:2048
	ds_read_b128 v[168:171], v168 offset:3072
	s_add_i32 m0, s46, 0xc000
	ds_read_b128 v[192:195], v190
	ds_read_b128 v[204:207], v190 offset:1024
	ds_read_b128 v[208:211], v190 offset:2048
	ds_read_b128 v[212:215], v190 offset:3072
	ds_read_b128 v[216:219], v190 offset:4096
	ds_read_b128 v[220:223], v190 offset:5120
	ds_read_b128 v[224:227], v190 offset:6144
	ds_read_b128 v[242:245], v190 offset:7168
	global_load_lds_dwordx4 v162, s[10:11]
	s_add_i32 m0, s46, 0xe000
	s_nop 0
	global_load_lds_dwordx4 v160, s[10:11]
	s_waitcnt vmcnt(8)
	s_waitcnt lgkmcnt(0)
	s_barrier
	s_setprio 1
	v_mfma_f32_16x16x32_bf16 v[126:129], v[130:133], v[192:195], v[126:129]
	v_mfma_f32_16x16x32_bf16 v[122:125], v[138:141], v[192:195], v[122:125]
	v_mfma_f32_16x16x32_bf16 v[110:113], v[130:133], v[208:211], v[110:113]
	v_mfma_f32_16x16x32_bf16 v[106:109], v[138:141], v[208:211], v[106:109]
	v_mfma_f32_16x16x32_bf16 v[94:97], v[130:133], v[216:219], v[94:97]
	v_mfma_f32_16x16x32_bf16 v[90:93], v[138:141], v[216:219], v[90:93]
	v_mfma_f32_16x16x32_bf16 v[78:81], v[130:133], v[224:227], v[78:81]
	v_mfma_f32_16x16x32_bf16 v[74:77], v[138:141], v[224:227], v[74:77]
	v_mfma_f32_16x16x32_bf16 v[126:129], v[134:137], v[204:207], v[126:129]
	v_mfma_f32_16x16x32_bf16 v[122:125], v[142:145], v[204:207], v[122:125]
	v_mfma_f32_16x16x32_bf16 v[110:113], v[134:137], v[212:215], v[110:113]
	v_mfma_f32_16x16x32_bf16 v[106:109], v[142:145], v[212:215], v[106:109]
	v_mfma_f32_16x16x32_bf16 v[94:97], v[134:137], v[220:223], v[94:97]
	v_mfma_f32_16x16x32_bf16 v[90:93], v[142:145], v[220:223], v[90:93]
	v_mfma_f32_16x16x32_bf16 v[78:81], v[134:137], v[242:245], v[78:81]
	v_mfma_f32_16x16x32_bf16 v[74:77], v[142:145], v[242:245], v[74:77]
	s_setprio 0
	s_setprio 1
	v_mfma_f32_16x16x32_bf16 v[118:121], v[146:149], v[192:195], v[118:121]
	v_mfma_f32_16x16x32_bf16 v[114:117], v[164:167], v[192:195], v[114:117]
	v_mfma_f32_16x16x32_bf16 v[102:105], v[146:149], v[208:211], v[102:105]
	v_mfma_f32_16x16x32_bf16 v[98:101], v[164:167], v[208:211], v[98:101]
	v_mfma_f32_16x16x32_bf16 v[86:89], v[146:149], v[216:219], v[86:89]
	v_mfma_f32_16x16x32_bf16 v[82:85], v[164:167], v[216:219], v[82:85]
	v_mfma_f32_16x16x32_bf16 v[70:73], v[146:149], v[224:227], v[70:73]
	v_mfma_f32_16x16x32_bf16 v[66:69], v[164:167], v[224:227], v[66:69]
	v_mfma_f32_16x16x32_bf16 v[118:121], v[150:153], v[204:207], v[118:121]
	v_mfma_f32_16x16x32_bf16 v[114:117], v[168:171], v[204:207], v[114:117]
	v_mfma_f32_16x16x32_bf16 v[102:105], v[150:153], v[212:215], v[102:105]
	v_mfma_f32_16x16x32_bf16 v[98:101], v[168:171], v[212:215], v[98:101]
	v_mfma_f32_16x16x32_bf16 v[86:89], v[150:153], v[220:223], v[86:89]
	v_mfma_f32_16x16x32_bf16 v[82:85], v[168:171], v[220:223], v[82:85]
	v_mfma_f32_16x16x32_bf16 v[70:73], v[150:153], v[242:245], v[70:73]
	v_mfma_f32_16x16x32_bf16 v[66:69], v[168:171], v[242:245], v[66:69]
	s_barrier
	s_setprio 0
	s_add_i32 s10, s39, s43
	s_mov_b32 m0, s10
	ds_read_b128 v[192:195], v190 offset:16384
	ds_read_b128 v[204:207], v190 offset:17408
	ds_read_b128 v[208:211], v190 offset:18432
	ds_read_b128 v[212:215], v190 offset:19456
	ds_read_b128 v[216:219], v190 offset:20480
	ds_read_b128 v[220:223], v190 offset:21504
	ds_read_b128 v[224:227], v190 offset:22528
	ds_read_b128 v[242:245], v190 offset:23552
	global_load_lds_dwordx4 v0, s[72:73]
	s_add_i32 m0, s10, 0x2000
	s_add_u32 s10, s72, 0xb0000
	s_addc_u32 s11, s73, 0
	s_add_i32 s30, s30, s43
	global_load_lds_dwordx4 v158, s[72:73]
	s_mov_b32 m0, s30
	s_nop 0
	global_load_lds_dwordx4 v0, s[10:11]
	s_add_i32 m0, s30, 0x2000
	s_nop 0
	global_load_lds_dwordx4 v158, s[10:11]
	s_mov_b32 m0, s46
	s_nop 0
	global_load_lds_dwordx4 v154, s[74:75]
	s_mov_b32 m0, s47
	s_nop 0
	global_load_lds_dwordx4 v156, s[74:75]
	s_waitcnt vmcnt(8)
	s_waitcnt lgkmcnt(0)
	s_barrier
	s_setprio 1
	v_mfma_f32_16x16x32_bf16 v[62:65], v[130:133], v[192:195], v[62:65]
	v_mfma_f32_16x16x32_bf16 v[58:61], v[138:141], v[192:195], v[58:61]
	v_mfma_f32_16x16x32_bf16 v[46:49], v[130:133], v[208:211], v[46:49]
	v_mfma_f32_16x16x32_bf16 v[42:45], v[138:141], v[208:211], v[42:45]
	v_mfma_f32_16x16x32_bf16 v[30:33], v[130:133], v[216:219], v[30:33]
	v_mfma_f32_16x16x32_bf16 v[26:29], v[138:141], v[216:219], v[26:29]
	v_mfma_f32_16x16x32_bf16 v[14:17], v[130:133], v[224:227], v[14:17]
	v_mfma_f32_16x16x32_bf16 v[10:13], v[138:141], v[224:227], v[10:13]
	v_mfma_f32_16x16x32_bf16 v[62:65], v[134:137], v[204:207], v[62:65]
	v_mfma_f32_16x16x32_bf16 v[58:61], v[142:145], v[204:207], v[58:61]
	v_mfma_f32_16x16x32_bf16 v[46:49], v[134:137], v[212:215], v[46:49]
	v_mfma_f32_16x16x32_bf16 v[42:45], v[142:145], v[212:215], v[42:45]
	v_mfma_f32_16x16x32_bf16 v[30:33], v[134:137], v[220:223], v[30:33]
	v_mfma_f32_16x16x32_bf16 v[26:29], v[142:145], v[220:223], v[26:29]
	v_mfma_f32_16x16x32_bf16 v[14:17], v[134:137], v[242:245], v[14:17]
	v_mfma_f32_16x16x32_bf16 v[10:13], v[142:145], v[242:245], v[10:13]
	s_setprio 0
	s_setprio 1
	v_mfma_f32_16x16x32_bf16 v[54:57], v[146:149], v[192:195], v[54:57]
	v_mfma_f32_16x16x32_bf16 v[50:53], v[164:167], v[192:195], v[50:53]
	v_mfma_f32_16x16x32_bf16 v[38:41], v[146:149], v[208:211], v[38:41]
	v_mfma_f32_16x16x32_bf16 v[34:37], v[164:167], v[208:211], v[34:37]
	v_mfma_f32_16x16x32_bf16 v[22:25], v[146:149], v[216:219], v[22:25]
	v_mfma_f32_16x16x32_bf16 v[18:21], v[164:167], v[216:219], v[18:21]
	v_mfma_f32_16x16x32_bf16 v[6:9], v[146:149], v[224:227], v[6:9]
	v_mfma_f32_16x16x32_bf16 v[2:5], v[164:167], v[224:227], v[2:5]
	v_mfma_f32_16x16x32_bf16 v[54:57], v[150:153], v[204:207], v[54:57]
	v_mfma_f32_16x16x32_bf16 v[50:53], v[168:171], v[204:207], v[50:53]
	v_mfma_f32_16x16x32_bf16 v[38:41], v[150:153], v[212:215], v[38:41]
	v_mfma_f32_16x16x32_bf16 v[34:37], v[168:171], v[212:215], v[34:37]
	v_mfma_f32_16x16x32_bf16 v[22:25], v[150:153], v[220:223], v[22:25]
	v_mfma_f32_16x16x32_bf16 v[18:21], v[168:171], v[220:223], v[18:21]
	v_mfma_f32_16x16x32_bf16 v[6:9], v[150:153], v[242:245], v[6:9]
	v_mfma_f32_16x16x32_bf16 v[2:5], v[168:171], v[242:245], v[2:5]
	s_barrier
; #define PG8_STAGE(bufoff, gbase, voff) do { _Pragma("unroll") for (int _i = 0; _i < 2; ++_i) \
;         __builtin_amdgcn_global_load_lds((const gunsigned*)((const gchar*)(gbase) + (voff)[_i]), (LAS unsigned*)(lds + (bufoff) + ldsw + _i * 8192), 16, 0, 0); } while (0)
; #define PG8_LDA(dst, b, h) do { _Pragma("unroll") for (int m = 0; m < 4; ++m) _Pragma("unroll") for (int k = 0; k < 2; ++k) dst[m][k] = *(const LAS bf16x8*)(lds + PG8_SA(b, h) + aoff + m * 2048 + k * 1024); } while (0)
; #define PG8_LDB(dst, b, h) do { _Pragma("unroll") for (int n = 0; n < 2; ++n) _Pragma("unroll") for (int k = 0; k < 2; ++k) dst[n][k] = *(const LAS bf16x8*)(lds + PG8_SB(b, h) + boff + n * 2048 + k * 1024); } while (0)
; #define PG8_MMA(ai, bj, At, Bt) do { __builtin_amdgcn_s_setprio(1); _Pragma("unroll") for (int m = 0; m < 4; ++m) _Pragma("unroll") for (int n = 0; n < 2; ++n) _Pragma("unroll") for (int k = 0; k < 2; ++k) \
;         acc[ai][bj][m][n] = __builtin_amdgcn_mfma_f32_16x16x32_bf16(Bt[n][k], At[m][k], acc[ai][bj][m][n], 0, 0, 0); __builtin_amdgcn_s_setprio(0); } while (0)
; #define PG8_WAIT_V(n) asm volatile("s_waitcnt vmcnt(" #n ")" ::: "memory")
; #define PG8_WAIT_L(n) asm volatile("s_waitcnt lgkmcnt(" #n ")" ::: "memory")
; #define PG8_BAR __builtin_amdgcn_s_barrier()
; #define PG8_SCHED __builtin_amdgcn_sched_barrier(0)
; template <class Epi, class Sched>
; __device__ __forceinline__ void gemm_phase(LAS unsigned char* lds, const int tid, const Gemm g, const Sched& S, const Epi& E) {
;     ...
;             const bool last = (t == nt - 2);
;             const gchar* a1 = cA + (size_t)(t + 1) * kstep;
;             const gchar* a2 = last ? nA : cA + (size_t)(t + 2) * kstep; const gchar* b2 = last ? nB : cB + (size_t)(t + 2) * kstep;
;             const gchar* a3 = a2 + kstep; const gchar* b3 = b2 + kstep;
;     ...
;             PG8_LDB(B0, 1, 0); PG8_LDB(B1, 1, 1); PG8_SCHED; PG8_LDA(At, 1, 0); PG8_STAGE(PG8_SA(0, 1), a2 + hstep, voffA);
;             PG8_WAIT_V(8); PG8_WAIT_L(0); PG8_BAR; PG8_MMA(0, 0, At, B0); PG8_MMA(0, 1, At, B1); PG8_BAR; PG8_SCHED;
;             PG8_LDA(At, 1, 1); PG8_STAGE(PG8_SB(1, 0), b3, voffB); PG8_STAGE(PG8_SB(1, 1), b3 + hstep, voffB); PG8_STAGE(PG8_SA(1, 0), a3, voffA);
;             PG8_WAIT_V(8); PG8_WAIT_L(0); PG8_BAR; PG8_MMA(1, 0, At, B0); PG8_MMA(1, 1, At, B1); PG8_BAR; PG8_SCHED;
	s_setprio 0
	s_add_i32 s30, 0, 0x18000
	s_add_i32 s39, 0, 0x1c000
	v_add_u32_e32 v142, s30, v174
	v_add_u32_e32 v168, s39, v174
	ds_read_b128 v[130:133], v142
	ds_read_b128 v[134:137], v142 offset:1024
	ds_read_b128 v[138:141], v142 offset:2048
	ds_read_b128 v[142:145], v142 offset:3072
	ds_read_b128 v[146:149], v168
	ds_read_b128 v[150:153], v168 offset:1024
	ds_read_b128 v[164:167], v168 offset:2048
	ds_read_b128 v[168:171], v168 offset:3072
	s_add_u32 s10, s74, 0xb0000
	s_addc_u32 s11, s75, 0
	s_mov_b32 m0, s48
	ds_read_b128 v[192:195], v190 offset:32768
	ds_read_b128 v[204:207], v190 offset:33792
	ds_read_b128 v[208:211], v190 offset:34816
	ds_read_b128 v[212:215], v190 offset:35840
	ds_read_b128 v[216:219], v190 offset:36864
	ds_read_b128 v[220:223], v190 offset:37888
	ds_read_b128 v[224:227], v190 offset:38912
	ds_read_b128 v[242:245], v190 offset:39936
	global_load_lds_dwordx4 v154, s[10:11]
	s_mov_b32 m0, s49
	s_nop 0
	global_load_lds_dwordx4 v156, s[10:11]
	s_waitcnt vmcnt(8)
	s_waitcnt lgkmcnt(0)
	s_barrier
	s_setprio 1
	v_mfma_f32_16x16x32_bf16 v[126:129], v[130:133], v[192:195], v[126:129]
	v_mfma_f32_16x16x32_bf16 v[122:125], v[138:141], v[192:195], v[122:125]
	v_mfma_f32_16x16x32_bf16 v[110:113], v[130:133], v[208:211], v[110:113]
	v_mfma_f32_16x16x32_bf16 v[106:109], v[138:141], v[208:211], v[106:109]
	v_mfma_f32_16x16x32_bf16 v[94:97], v[130:133], v[216:219], v[94:97]
	v_mfma_f32_16x16x32_bf16 v[90:93], v[138:141], v[216:219], v[90:93]
	v_mfma_f32_16x16x32_bf16 v[78:81], v[130:133], v[224:227], v[78:81]
	v_mfma_f32_16x16x32_bf16 v[74:77], v[138:141], v[224:227], v[74:77]
	v_mfma_f32_16x16x32_bf16 v[126:129], v[134:137], v[204:207], v[126:129]
	v_mfma_f32_16x16x32_bf16 v[122:125], v[142:145], v[204:207], v[122:125]
	v_mfma_f32_16x16x32_bf16 v[110:113], v[134:137], v[212:215], v[110:113]
	v_mfma_f32_16x16x32_bf16 v[106:109], v[142:145], v[212:215], v[106:109]
	v_mfma_f32_16x16x32_bf16 v[94:97], v[134:137], v[220:223], v[94:97]
	v_mfma_f32_16x16x32_bf16 v[90:93], v[142:145], v[220:223], v[90:93]
	v_mfma_f32_16x16x32_bf16 v[78:81], v[134:137], v[242:245], v[78:81]
	v_mfma_f32_16x16x32_bf16 v[74:77], v[142:145], v[242:245], v[74:77]
	s_setprio 0
	s_setprio 1
	v_mfma_f32_16x16x32_bf16 v[118:121], v[146:149], v[192:195], v[118:121]
	v_mfma_f32_16x16x32_bf16 v[114:117], v[164:167], v[192:195], v[114:117]
	v_mfma_f32_16x16x32_bf16 v[102:105], v[146:149], v[208:211], v[102:105]
	v_mfma_f32_16x16x32_bf16 v[98:101], v[164:167], v[208:211], v[98:101]
	v_mfma_f32_16x16x32_bf16 v[86:89], v[146:149], v[216:219], v[86:89]
	v_mfma_f32_16x16x32_bf16 v[82:85], v[164:167], v[216:219], v[82:85]
	v_mfma_f32_16x16x32_bf16 v[70:73], v[146:149], v[224:227], v[70:73]
	v_mfma_f32_16x16x32_bf16 v[66:69], v[164:167], v[224:227], v[66:69]
	v_mfma_f32_16x16x32_bf16 v[118:121], v[150:153], v[204:207], v[118:121]
	v_mfma_f32_16x16x32_bf16 v[114:117], v[168:171], v[204:207], v[114:117]
	v_mfma_f32_16x16x32_bf16 v[102:105], v[150:153], v[212:215], v[102:105]
	v_mfma_f32_16x16x32_bf16 v[98:101], v[168:171], v[212:215], v[98:101]
	v_mfma_f32_16x16x32_bf16 v[86:89], v[150:153], v[220:223], v[86:89]
	v_mfma_f32_16x16x32_bf16 v[82:85], v[168:171], v[220:223], v[82:85]
	v_mfma_f32_16x16x32_bf16 v[70:73], v[150:153], v[242:245], v[70:73]
	v_mfma_f32_16x16x32_bf16 v[66:69], v[168:171], v[242:245], v[66:69]
	s_barrier
	s_setprio 0
	s_add_i32 s10, s30, s43
	s_mov_b32 m0, s10
	ds_read_b128 v[192:195], v190 offset:49152
	ds_read_b128 v[204:207], v190 offset:50176
	ds_read_b128 v[208:211], v190 offset:51200
	ds_read_b128 v[212:215], v190 offset:52224
	ds_read_b128 v[216:219], v190 offset:53248
	ds_read_b128 v[220:223], v190 offset:54272
	ds_read_b128 v[224:227], v190 offset:55296
	ds_read_b128 v[242:245], v190 offset:56320
	global_load_lds_dwordx4 v201, s[72:73]
	s_add_i32 m0, s10, 0x2000
	s_add_u32 s10, s72, 0xb0080
	s_addc_u32 s11, s73, 0
	s_add_i32 s30, s39, s43
	global_load_lds_dwordx4 v247, s[72:73]
	s_mov_b32 m0, s30
	s_nop 0
	global_load_lds_dwordx4 v0, s[10:11]
	s_add_i32 m0, s30, 0x2000
	s_nop 0
	global_load_lds_dwordx4 v158, s[10:11]
	s_mov_b32 m0, s53
	s_nop 0
	global_load_lds_dwordx4 v249, s[74:75]
	s_mov_b32 m0, s54
	s_nop 0
	global_load_lds_dwordx4 v251, s[74:75]
	s_waitcnt vmcnt(8)
	s_waitcnt lgkmcnt(0)
	s_barrier
	s_setprio 1
	v_mfma_f32_16x16x32_bf16 v[62:65], v[130:133], v[192:195], v[62:65]
	v_mfma_f32_16x16x32_bf16 v[58:61], v[138:141], v[192:195], v[58:61]
	v_mfma_f32_16x16x32_bf16 v[46:49], v[130:133], v[208:211], v[46:49]
	v_mfma_f32_16x16x32_bf16 v[42:45], v[138:141], v[208:211], v[42:45]
	v_mfma_f32_16x16x32_bf16 v[30:33], v[130:133], v[216:219], v[30:33]
	v_mfma_f32_16x16x32_bf16 v[26:29], v[138:141], v[216:219], v[26:29]
	v_mfma_f32_16x16x32_bf16 v[14:17], v[130:133], v[224:227], v[14:17]
	v_mfma_f32_16x16x32_bf16 v[10:13], v[138:141], v[224:227], v[10:13]
	v_mfma_f32_16x16x32_bf16 v[62:65], v[134:137], v[204:207], v[62:65]
	v_mfma_f32_16x16x32_bf16 v[58:61], v[142:145], v[204:207], v[58:61]
	v_mfma_f32_16x16x32_bf16 v[46:49], v[134:137], v[212:215], v[46:49]
	v_mfma_f32_16x16x32_bf16 v[42:45], v[142:145], v[212:215], v[42:45]
	v_mfma_f32_16x16x32_bf16 v[30:33], v[134:137], v[220:223], v[30:33]
	v_mfma_f32_16x16x32_bf16 v[26:29], v[142:145], v[220:223], v[26:29]
	v_mfma_f32_16x16x32_bf16 v[14:17], v[134:137], v[242:245], v[14:17]
	v_mfma_f32_16x16x32_bf16 v[10:13], v[142:145], v[242:245], v[10:13]
	s_setprio 0
	s_setprio 1
	s_add_i32 s29, s29, 2
	s_add_u32 s31, s31, 0x100
	s_addc_u32 s93, s93, 0
	s_cmp_gt_u32 s29, 41
	s_mov_b64 s[10:11], vcc
	s_cbranch_scc1 .Lrot_skip_319
	s_add_u32 vcc_lo, s10, 0x100
	s_addc_u32 vcc_hi, s11, 0
	s_cmp_eq_u32 s29, 40
	s_cselect_b32 s75, s21, vcc_hi
	s_cselect_b32 s74, s20, vcc_lo
	s_cselect_b32 s73, s1, s93
	s_cselect_b32 s72, s0, s31
.Lrot_skip_319:
	s_cmp_gt_u32 s29, 41
	v_mfma_f32_16x16x32_bf16 v[54:57], v[146:149], v[192:195], v[54:57]
	v_mfma_f32_16x16x32_bf16 v[50:53], v[164:167], v[192:195], v[50:53]
	v_mfma_f32_16x16x32_bf16 v[38:41], v[146:149], v[208:211], v[38:41]
	v_mfma_f32_16x16x32_bf16 v[34:37], v[164:167], v[208:211], v[34:37]
	v_mfma_f32_16x16x32_bf16 v[22:25], v[146:149], v[216:219], v[22:25]
	v_mfma_f32_16x16x32_bf16 v[18:21], v[164:167], v[216:219], v[18:21]
	v_mfma_f32_16x16x32_bf16 v[6:9], v[146:149], v[224:227], v[6:9]
	v_mfma_f32_16x16x32_bf16 v[2:5], v[164:167], v[224:227], v[2:5]
	v_mfma_f32_16x16x32_bf16 v[54:57], v[150:153], v[204:207], v[54:57]
	v_mfma_f32_16x16x32_bf16 v[50:53], v[168:171], v[204:207], v[50:53]
	v_mfma_f32_16x16x32_bf16 v[38:41], v[150:153], v[212:215], v[38:41]
	v_mfma_f32_16x16x32_bf16 v[34:37], v[168:171], v[212:215], v[34:37]
	v_mfma_f32_16x16x32_bf16 v[22:25], v[150:153], v[220:223], v[22:25]
	v_mfma_f32_16x16x32_bf16 v[18:21], v[168:171], v[220:223], v[18:21]
	v_mfma_f32_16x16x32_bf16 v[6:9], v[150:153], v[242:245], v[6:9]
	v_mfma_f32_16x16x32_bf16 v[2:5], v[168:171], v[242:245], v[2:5]
	s_barrier
	s_setprio 0
	s_cbranch_scc0 .Lrot_319
	s_and_b64 vcc, exec, s[16:17]
	s_cbranch_vccz .LBB0_322
	s_barrier

; #define PG8_STAGE(bufoff, gbase, voff) do { _Pragma("unroll") for (int _i = 0; _i < 2; ++_i) \
;         __builtin_amdgcn_global_load_lds((const gunsigned*)((const gchar*)(gbase) + (voff)[_i]), (LAS unsigned*)(lds + (bufoff) + ldsw + _i * 8192), 16, 0, 0); } while (0)
; #define PG8_LDA(dst, b, h) do { _Pragma("unroll") for (int m = 0; m < 4; ++m) _Pragma("unroll") for (int k = 0; k < 2; ++k) dst[m][k] = *(const LAS bf16x8*)(lds + PG8_SA(b, h) + aoff + m * 2048 + k * 1024); } while (0)
; #define PG8_LDB(dst, b, h) do { _Pragma("unroll") for (int n = 0; n < 2; ++n) _Pragma("unroll") for (int k = 0; k < 2; ++k) dst[n][k] = *(const LAS bf16x8*)(lds + PG8_SB(b, h) + boff + n * 2048 + k * 1024); } while (0)
; #define PG8_MMA(ai, bj, At, Bt) do { __builtin_amdgcn_s_setprio(1); _Pragma("unroll") for (int m = 0; m < 4; ++m) _Pragma("unroll") for (int n = 0; n < 2; ++n) _Pragma("unroll") for (int k = 0; k < 2; ++k) \
;         acc[ai][bj][m][n] = __builtin_amdgcn_mfma_f32_16x16x32_bf16(Bt[n][k], At[m][k], acc[ai][bj][m][n], 0, 0, 0); __builtin_amdgcn_s_setprio(0); } while (0)
; #define PG8_WAIT_V(n) asm volatile("s_waitcnt vmcnt(" #n ")" ::: "memory")
; #define PG8_WAIT_L(n) asm volatile("s_waitcnt lgkmcnt(" #n ")" ::: "memory")
; #define PG8_BAR __builtin_amdgcn_s_barrier()
; #define PG8_SCHED __builtin_amdgcn_sched_barrier(0)
; template <class Epi, class Sched>
; __device__ __forceinline__ void gemm_phase(LAS unsigned char* lds, const int tid, const Gemm g, const Sched& S, const Epi& E) {
;     ...
;         for (int t = 0; t < nt; t += 2) {
;             const bool last = (t == nt - 2);
;             const gchar* a1 = cA + (size_t)(t + 1) * kstep;
;             const gchar* a2 = last ? nA : cA + (size_t)(t + 2) * kstep; const gchar* b2 = last ? nB : cB + (size_t)(t + 2) * kstep;
;             const gchar* a3 = a2 + kstep; const gchar* b3 = b2 + kstep;
;             PG8_LDB(B0, 0, 0); PG8_LDB(B1, 0, 1); PG8_SCHED; PG8_LDA(At, 0, 0); PG8_STAGE(PG8_SA(1, 1), a1 + hstep, voffA);
;             PG8_WAIT_V(8); PG8_WAIT_L(0); PG8_BAR; PG8_MMA(0, 0, At, B0); PG8_MMA(0, 1, At, B1); PG8_BAR; PG8_SCHED;
;             PG8_LDA(At, 0, 1); PG8_STAGE(PG8_SB(0, 0), b2, voffB); PG8_STAGE(PG8_SB(0, 1), b2 + hstep, voffB); PG8_STAGE(PG8_SA(0, 0), a2, voffA);
;             PG8_WAIT_V(8); PG8_WAIT_L(0); PG8_BAR; PG8_MMA(1, 0, At, B0); PG8_MMA(1, 1, At, B1); PG8_BAR; PG8_SCHED;
.LBB0_369:
	s_add_u32 s20, s16, 0xfffc0080
	s_addc_u32 s21, s17, -1
	s_cmp_eq_u32 s31, 12
	s_cselect_b32 s57, s11, s21
	s_cselect_b32 s56, s12, s20
	s_cselect_b32 s21, s9, s24
	s_cselect_b32 s20, s15, s23
.Lrot_369:
	s_add_i32 s29, 0, 0x10000
	v_add_u32_e32 v140, s29, v145
	s_add_i32 s30, 0, 0x14000
	ds_read_b128 v[146:149], v140
	ds_read_b128 v[156:159], v140 offset:1024
	ds_read_b128 v[160:163], v140 offset:2048
	ds_read_b128 v[164:167], v140 offset:3072
	v_add_u32_e32 v140, s30, v145
	ds_read_b128 v[168:171], v140
	ds_read_b128 v[172:175], v140 offset:1024
	ds_read_b128 v[176:179], v140 offset:2048
	ds_read_b128 v[180:183], v140 offset:3072
	s_add_i32 m0, s73, 0xc000
	ds_read_b128 v[184:187], v155
	ds_read_b128 v[188:191], v155 offset:1024
	ds_read_b128 v[192:195], v155 offset:2048
	ds_read_b128 v[204:207], v155 offset:3072
	ds_read_b128 v[208:211], v155 offset:4096
	ds_read_b128 v[212:215], v155 offset:5120
	ds_read_b128 v[216:219], v155 offset:6144
	ds_read_b128 v[220:223], v155 offset:7168
	global_load_lds_dwordx4 v138, s[16:17]
	s_add_i32 m0, s73, 0xe000
	s_nop 0
	global_load_lds_dwordx4 v136, s[16:17]
	s_waitcnt vmcnt(8)
	s_waitcnt lgkmcnt(0)
	s_barrier
	s_setprio 1
	v_mfma_f32_16x16x32_bf16 v[126:129], v[146:149], v[184:187], v[126:129]
	v_mfma_f32_16x16x32_bf16 v[118:121], v[160:163], v[184:187], v[118:121]
	v_mfma_f32_16x16x32_bf16 v[110:113], v[146:149], v[192:195], v[110:113]
	v_mfma_f32_16x16x32_bf16 v[102:105], v[160:163], v[192:195], v[102:105]
	v_mfma_f32_16x16x32_bf16 v[94:97], v[146:149], v[208:211], v[94:97]
	v_mfma_f32_16x16x32_bf16 v[86:89], v[160:163], v[208:211], v[86:89]
	v_mfma_f32_16x16x32_bf16 v[78:81], v[146:149], v[216:219], v[78:81]
	v_mfma_f32_16x16x32_bf16 v[70:73], v[160:163], v[216:219], v[70:73]
	v_mfma_f32_16x16x32_bf16 v[126:129], v[156:159], v[188:191], v[126:129]
	v_mfma_f32_16x16x32_bf16 v[118:121], v[164:167], v[188:191], v[118:121]
	v_mfma_f32_16x16x32_bf16 v[110:113], v[156:159], v[204:207], v[110:113]
	v_mfma_f32_16x16x32_bf16 v[102:105], v[164:167], v[204:207], v[102:105]
	v_mfma_f32_16x16x32_bf16 v[94:97], v[156:159], v[212:215], v[94:97]
	v_mfma_f32_16x16x32_bf16 v[86:89], v[164:167], v[212:215], v[86:89]
	v_mfma_f32_16x16x32_bf16 v[78:81], v[156:159], v[220:223], v[78:81]
	v_mfma_f32_16x16x32_bf16 v[70:73], v[164:167], v[220:223], v[70:73]
	s_setprio 0
	s_setprio 1
	v_mfma_f32_16x16x32_bf16 v[122:125], v[168:171], v[184:187], v[122:125]
	v_mfma_f32_16x16x32_bf16 v[114:117], v[176:179], v[184:187], v[114:117]
	v_mfma_f32_16x16x32_bf16 v[106:109], v[168:171], v[192:195], v[106:109]
	v_mfma_f32_16x16x32_bf16 v[98:101], v[176:179], v[192:195], v[98:101]
	v_mfma_f32_16x16x32_bf16 v[90:93], v[168:171], v[208:211], v[90:93]
	v_mfma_f32_16x16x32_bf16 v[82:85], v[176:179], v[208:211], v[82:85]
	v_mfma_f32_16x16x32_bf16 v[74:77], v[168:171], v[216:219], v[74:77]
	v_mfma_f32_16x16x32_bf16 v[66:69], v[176:179], v[216:219], v[66:69]
	v_mfma_f32_16x16x32_bf16 v[122:125], v[172:175], v[188:191], v[122:125]
	v_mfma_f32_16x16x32_bf16 v[114:117], v[180:183], v[188:191], v[114:117]
	v_mfma_f32_16x16x32_bf16 v[106:109], v[172:175], v[204:207], v[106:109]
	v_mfma_f32_16x16x32_bf16 v[98:101], v[180:183], v[204:207], v[98:101]
	v_mfma_f32_16x16x32_bf16 v[90:93], v[172:175], v[212:215], v[90:93]
	v_mfma_f32_16x16x32_bf16 v[82:85], v[180:183], v[212:215], v[82:85]
	v_mfma_f32_16x16x32_bf16 v[74:77], v[172:175], v[220:223], v[74:77]
	v_mfma_f32_16x16x32_bf16 v[66:69], v[180:183], v[220:223], v[66:69]
	s_barrier
	s_setprio 0
	s_add_i32 s29, s29, s43
	s_mov_b32 m0, s29
	ds_read_b128 v[184:187], v155 offset:16384
	ds_read_b128 v[188:191], v155 offset:17408
	ds_read_b128 v[192:195], v155 offset:18432
	ds_read_b128 v[204:207], v155 offset:19456
	ds_read_b128 v[208:211], v155 offset:20480
	ds_read_b128 v[212:215], v155 offset:21504
	ds_read_b128 v[216:219], v155 offset:22528
	ds_read_b128 v[220:223], v155 offset:23552
	global_load_lds_dwordx4 v0, s[20:21]
	s_add_i32 m0, s29, 0x2000
	s_add_u32 s46, s20, 0x40000
	s_addc_u32 s47, s21, 0
	s_add_i32 s29, s30, s43
	global_load_lds_dwordx4 v130, s[20:21]
	s_mov_b32 m0, s29
	s_nop 0
	global_load_lds_dwordx4 v0, s[46:47]
	s_add_i32 m0, s29, 0x2000
	s_nop 0
	global_load_lds_dwordx4 v130, s[46:47]
	s_mov_b32 m0, s73
	s_nop 0
	global_load_lds_dwordx4 v134, s[56:57]
	s_mov_b32 m0, s74
	s_nop 0
	global_load_lds_dwordx4 v132, s[56:57]
	s_waitcnt vmcnt(8)
	s_waitcnt lgkmcnt(0)
	s_barrier
	s_setprio 1
	v_mfma_f32_16x16x32_bf16 v[62:65], v[146:149], v[184:187], v[62:65]
	v_mfma_f32_16x16x32_bf16 v[54:57], v[160:163], v[184:187], v[54:57]
	v_mfma_f32_16x16x32_bf16 v[46:49], v[146:149], v[192:195], v[46:49]
	v_mfma_f32_16x16x32_bf16 v[38:41], v[160:163], v[192:195], v[38:41]
	v_mfma_f32_16x16x32_bf16 v[30:33], v[146:149], v[208:211], v[30:33]
	v_mfma_f32_16x16x32_bf16 v[22:25], v[160:163], v[208:211], v[22:25]
	v_mfma_f32_16x16x32_bf16 v[14:17], v[146:149], v[216:219], v[14:17]
	v_mfma_f32_16x16x32_bf16 v[6:9], v[160:163], v[216:219], v[6:9]
	v_mfma_f32_16x16x32_bf16 v[62:65], v[156:159], v[188:191], v[62:65]
	v_mfma_f32_16x16x32_bf16 v[54:57], v[164:167], v[188:191], v[54:57]
	v_mfma_f32_16x16x32_bf16 v[46:49], v[156:159], v[204:207], v[46:49]
	v_mfma_f32_16x16x32_bf16 v[38:41], v[164:167], v[204:207], v[38:41]
	v_mfma_f32_16x16x32_bf16 v[30:33], v[156:159], v[212:215], v[30:33]
	v_mfma_f32_16x16x32_bf16 v[22:25], v[164:167], v[212:215], v[22:25]
	v_mfma_f32_16x16x32_bf16 v[14:17], v[156:159], v[220:223], v[14:17]
	v_mfma_f32_16x16x32_bf16 v[6:9], v[164:167], v[220:223], v[6:9]
	s_setprio 0
	s_setprio 1
	v_mfma_f32_16x16x32_bf16 v[58:61], v[168:171], v[184:187], v[58:61]
	v_mfma_f32_16x16x32_bf16 v[50:53], v[176:179], v[184:187], v[50:53]
	v_mfma_f32_16x16x32_bf16 v[42:45], v[168:171], v[192:195], v[42:45]
	v_mfma_f32_16x16x32_bf16 v[34:37], v[176:179], v[192:195], v[34:37]
	v_mfma_f32_16x16x32_bf16 v[26:29], v[168:171], v[208:211], v[26:29]
	v_mfma_f32_16x16x32_bf16 v[18:21], v[176:179], v[208:211], v[18:21]
	v_mfma_f32_16x16x32_bf16 v[10:13], v[168:171], v[216:219], v[10:13]
	v_mfma_f32_16x16x32_bf16 v[2:5], v[176:179], v[216:219], v[2:5]
	v_mfma_f32_16x16x32_bf16 v[58:61], v[172:175], v[188:191], v[58:61]
	v_mfma_f32_16x16x32_bf16 v[50:53], v[180:183], v[188:191], v[50:53]
	v_mfma_f32_16x16x32_bf16 v[42:45], v[172:175], v[204:207], v[42:45]
	v_mfma_f32_16x16x32_bf16 v[34:37], v[180:183], v[204:207], v[34:37]
	v_mfma_f32_16x16x32_bf16 v[26:29], v[172:175], v[212:215], v[26:29]
	v_mfma_f32_16x16x32_bf16 v[18:21], v[180:183], v[212:215], v[18:21]
	v_mfma_f32_16x16x32_bf16 v[10:13], v[172:175], v[220:223], v[10:13]
	v_mfma_f32_16x16x32_bf16 v[2:5], v[180:183], v[220:223], v[2:5]
	s_barrier
; #define PG8_STAGE(bufoff, gbase, voff) do { _Pragma("unroll") for (int _i = 0; _i < 2; ++_i) \
;         __builtin_amdgcn_global_load_lds((const gunsigned*)((const gchar*)(gbase) + (voff)[_i]), (LAS unsigned*)(lds + (bufoff) + ldsw + _i * 8192), 16, 0, 0); } while (0)
; #define PG8_LDA(dst, b, h) do { _Pragma("unroll") for (int m = 0; m < 4; ++m) _Pragma("unroll") for (int k = 0; k < 2; ++k) dst[m][k] = *(const LAS bf16x8*)(lds + PG8_SA(b, h) + aoff + m * 2048 + k * 1024); } while (0)
; #define PG8_LDB(dst, b, h) do { _Pragma("unroll") for (int n = 0; n < 2; ++n) _Pragma("unroll") for (int k = 0; k < 2; ++k) dst[n][k] = *(const LAS bf16x8*)(lds + PG8_SB(b, h) + boff + n * 2048 + k * 1024); } while (0)
; #define PG8_MMA(ai, bj, At, Bt) do { __builtin_amdgcn_s_setprio(1); _Pragma("unroll") for (int m = 0; m < 4; ++m) _Pragma("unroll") for (int n = 0; n < 2; ++n) _Pragma("unroll") for (int k = 0; k < 2; ++k) \
;         acc[ai][bj][m][n] = __builtin_amdgcn_mfma_f32_16x16x32_bf16(Bt[n][k], At[m][k], acc[ai][bj][m][n], 0, 0, 0); __builtin_amdgcn_s_setprio(0); } while (0)
; #define PG8_WAIT_V(n) asm volatile("s_waitcnt vmcnt(" #n ")" ::: "memory")
; #define PG8_WAIT_L(n) asm volatile("s_waitcnt lgkmcnt(" #n ")" ::: "memory")
; #define PG8_BAR __builtin_amdgcn_s_barrier()
; #define PG8_SCHED __builtin_amdgcn_sched_barrier(0)
; template <class Epi, class Sched>
; __device__ __forceinline__ void gemm_phase(LAS unsigned char* lds, const int tid, const Gemm g, const Sched& S, const Epi& E) {
;     ...
;             const bool last = (t == nt - 2);
;             const gchar* a1 = cA + (size_t)(t + 1) * kstep;
;             const gchar* a2 = last ? nA : cA + (size_t)(t + 2) * kstep; const gchar* b2 = last ? nB : cB + (size_t)(t + 2) * kstep;
;             const gchar* a3 = a2 + kstep; const gchar* b3 = b2 + kstep;
;     ...
;             PG8_LDB(B0, 1, 0); PG8_LDB(B1, 1, 1); PG8_SCHED; PG8_LDA(At, 1, 0); PG8_STAGE(PG8_SA(0, 1), a2 + hstep, voffA);
;             PG8_WAIT_V(8); PG8_WAIT_L(0); PG8_BAR; PG8_MMA(0, 0, At, B0); PG8_MMA(0, 1, At, B1); PG8_BAR; PG8_SCHED;
;             PG8_LDA(At, 1, 1); PG8_STAGE(PG8_SB(1, 0), b3, voffB); PG8_STAGE(PG8_SB(1, 1), b3 + hstep, voffB); PG8_STAGE(PG8_SA(1, 0), a3, voffA);
;             PG8_WAIT_V(8); PG8_WAIT_L(0); PG8_BAR; PG8_MMA(1, 0, At, B0); PG8_MMA(1, 1, At, B1); PG8_BAR; PG8_SCHED;
	s_setprio 0
	s_add_i32 s29, 0, 0x18000
	v_add_u32_e32 v142, s29, v145
	s_add_i32 s30, 0, 0x1c000
	ds_read_b128 v[146:149], v142
	ds_read_b128 v[156:159], v142 offset:1024
	ds_read_b128 v[160:163], v142 offset:2048
	ds_read_b128 v[164:167], v142 offset:3072
	v_add_u32_e32 v142, s30, v145
	ds_read_b128 v[168:171], v142
	ds_read_b128 v[172:175], v142 offset:1024
	ds_read_b128 v[176:179], v142 offset:2048
	ds_read_b128 v[180:183], v142 offset:3072
	s_add_u32 s46, s56, 0x40000
	s_addc_u32 s47, s57, 0
	s_mov_b32 m0, s75
	ds_read_b128 v[184:187], v155 offset:32768
	ds_read_b128 v[188:191], v155 offset:33792
	ds_read_b128 v[192:195], v155 offset:34816
	ds_read_b128 v[204:207], v155 offset:35840
	ds_read_b128 v[208:211], v155 offset:36864
	ds_read_b128 v[212:215], v155 offset:37888
	ds_read_b128 v[216:219], v155 offset:38912
	ds_read_b128 v[220:223], v155 offset:39936
	global_load_lds_dwordx4 v134, s[46:47]
	s_mov_b32 m0, s92
	s_nop 0
	global_load_lds_dwordx4 v132, s[46:47]
	s_waitcnt vmcnt(8)
	s_waitcnt lgkmcnt(0)
	s_barrier
	s_setprio 1
	v_mfma_f32_16x16x32_bf16 v[126:129], v[146:149], v[184:187], v[126:129]
	v_mfma_f32_16x16x32_bf16 v[118:121], v[160:163], v[184:187], v[118:121]
	v_mfma_f32_16x16x32_bf16 v[110:113], v[146:149], v[192:195], v[110:113]
	v_mfma_f32_16x16x32_bf16 v[102:105], v[160:163], v[192:195], v[102:105]
	v_mfma_f32_16x16x32_bf16 v[94:97], v[146:149], v[208:211], v[94:97]
	v_mfma_f32_16x16x32_bf16 v[86:89], v[160:163], v[208:211], v[86:89]
	v_mfma_f32_16x16x32_bf16 v[78:81], v[146:149], v[216:219], v[78:81]
	v_mfma_f32_16x16x32_bf16 v[70:73], v[160:163], v[216:219], v[70:73]
	v_mfma_f32_16x16x32_bf16 v[126:129], v[156:159], v[188:191], v[126:129]
	v_mfma_f32_16x16x32_bf16 v[118:121], v[164:167], v[188:191], v[118:121]
	v_mfma_f32_16x16x32_bf16 v[110:113], v[156:159], v[204:207], v[110:113]
	v_mfma_f32_16x16x32_bf16 v[102:105], v[164:167], v[204:207], v[102:105]
	v_mfma_f32_16x16x32_bf16 v[94:97], v[156:159], v[212:215], v[94:97]
	v_mfma_f32_16x16x32_bf16 v[86:89], v[164:167], v[212:215], v[86:89]
	v_mfma_f32_16x16x32_bf16 v[78:81], v[156:159], v[220:223], v[78:81]
	v_mfma_f32_16x16x32_bf16 v[70:73], v[164:167], v[220:223], v[70:73]
	s_setprio 0
	s_setprio 1
	v_mfma_f32_16x16x32_bf16 v[122:125], v[168:171], v[184:187], v[122:125]
	v_mfma_f32_16x16x32_bf16 v[114:117], v[176:179], v[184:187], v[114:117]
	v_mfma_f32_16x16x32_bf16 v[106:109], v[168:171], v[192:195], v[106:109]
	v_mfma_f32_16x16x32_bf16 v[98:101], v[176:179], v[192:195], v[98:101]
	v_mfma_f32_16x16x32_bf16 v[90:93], v[168:171], v[208:211], v[90:93]
	v_mfma_f32_16x16x32_bf16 v[82:85], v[176:179], v[208:211], v[82:85]
	v_mfma_f32_16x16x32_bf16 v[74:77], v[168:171], v[216:219], v[74:77]
	v_mfma_f32_16x16x32_bf16 v[66:69], v[176:179], v[216:219], v[66:69]
	v_mfma_f32_16x16x32_bf16 v[122:125], v[172:175], v[188:191], v[122:125]
	v_mfma_f32_16x16x32_bf16 v[114:117], v[180:183], v[188:191], v[114:117]
	v_mfma_f32_16x16x32_bf16 v[106:109], v[172:175], v[204:207], v[106:109]
	v_mfma_f32_16x16x32_bf16 v[98:101], v[180:183], v[204:207], v[98:101]
	v_mfma_f32_16x16x32_bf16 v[90:93], v[172:175], v[212:215], v[90:93]
	v_mfma_f32_16x16x32_bf16 v[82:85], v[180:183], v[212:215], v[82:85]
	v_mfma_f32_16x16x32_bf16 v[74:77], v[172:175], v[220:223], v[74:77]
	v_mfma_f32_16x16x32_bf16 v[66:69], v[180:183], v[220:223], v[66:69]
	s_barrier
	s_setprio 0
	s_add_i32 s29, s29, s43
	s_mov_b32 m0, s29
	ds_read_b128 v[184:187], v155 offset:49152
	ds_read_b128 v[188:191], v155 offset:50176
	ds_read_b128 v[192:195], v155 offset:51200
	ds_read_b128 v[204:207], v155 offset:52224
	ds_read_b128 v[208:211], v155 offset:53248
	ds_read_b128 v[212:215], v155 offset:54272
	ds_read_b128 v[216:219], v155 offset:55296
	ds_read_b128 v[220:223], v155 offset:56320
	global_load_lds_dwordx4 v141, s[20:21]
	s_add_i32 m0, s29, 0x2000
	s_add_i32 s29, s30, s43
	global_load_lds_dwordx4 v153, s[20:21]
	s_add_u32 s20, s20, 0x40080
	s_addc_u32 s21, s21, 0
	s_mov_b32 m0, s29
	s_nop 0
	global_load_lds_dwordx4 v0, s[20:21]
	s_add_i32 m0, s29, 0x2000
	s_nop 0
	global_load_lds_dwordx4 v130, s[20:21]
	s_mov_b32 m0, s93
	s_nop 0
	global_load_lds_dwordx4 v201, s[56:57]
	s_mov_b32 m0, s44
	s_nop 0
	global_load_lds_dwordx4 v225, s[56:57]
	s_waitcnt vmcnt(8)
	s_waitcnt lgkmcnt(0)
	s_barrier
	s_setprio 1
	v_mfma_f32_16x16x32_bf16 v[62:65], v[146:149], v[184:187], v[62:65]
	v_mfma_f32_16x16x32_bf16 v[54:57], v[160:163], v[184:187], v[54:57]
	v_mfma_f32_16x16x32_bf16 v[46:49], v[146:149], v[192:195], v[46:49]
	v_mfma_f32_16x16x32_bf16 v[38:41], v[160:163], v[192:195], v[38:41]
	v_mfma_f32_16x16x32_bf16 v[30:33], v[146:149], v[208:211], v[30:33]
	v_mfma_f32_16x16x32_bf16 v[22:25], v[160:163], v[208:211], v[22:25]
	v_mfma_f32_16x16x32_bf16 v[14:17], v[146:149], v[216:219], v[14:17]
	v_mfma_f32_16x16x32_bf16 v[6:9], v[160:163], v[216:219], v[6:9]
	v_mfma_f32_16x16x32_bf16 v[62:65], v[156:159], v[188:191], v[62:65]
	v_mfma_f32_16x16x32_bf16 v[54:57], v[164:167], v[188:191], v[54:57]
	v_mfma_f32_16x16x32_bf16 v[46:49], v[156:159], v[204:207], v[46:49]
	v_mfma_f32_16x16x32_bf16 v[38:41], v[164:167], v[204:207], v[38:41]
	v_mfma_f32_16x16x32_bf16 v[30:33], v[156:159], v[212:215], v[30:33]
	v_mfma_f32_16x16x32_bf16 v[22:25], v[164:167], v[212:215], v[22:25]
	v_mfma_f32_16x16x32_bf16 v[14:17], v[156:159], v[220:223], v[14:17]
	v_mfma_f32_16x16x32_bf16 v[6:9], v[164:167], v[220:223], v[6:9]
	s_setprio 0
	s_setprio 1
	s_add_i32 s31, s31, 2
	s_add_u32 s23, s23, 0x100
	s_addc_u32 s24, s24, 0
	s_add_u32 s16, s16, 0x100
	s_addc_u32 s17, s17, 0
	s_cmp_gt_u32 s31, 13
	s_cbranch_scc1 .Lrot_skip_369
	s_add_u32 s20, s16, 0xfffc0080
	s_addc_u32 s21, s17, -1
	s_cmp_eq_u32 s31, 12
	s_cselect_b32 s57, s11, s21
	s_cselect_b32 s56, s12, s20
	s_cselect_b32 s21, s9, s24
	s_cselect_b32 s20, s15, s23
.Lrot_skip_369:
	s_cmp_gt_u32 s31, 13
	v_mfma_f32_16x16x32_bf16 v[58:61], v[168:171], v[184:187], v[58:61]
	v_mfma_f32_16x16x32_bf16 v[50:53], v[176:179], v[184:187], v[50:53]
	v_mfma_f32_16x16x32_bf16 v[42:45], v[168:171], v[192:195], v[42:45]
	v_mfma_f32_16x16x32_bf16 v[34:37], v[176:179], v[192:195], v[34:37]
	v_mfma_f32_16x16x32_bf16 v[26:29], v[168:171], v[208:211], v[26:29]
	v_mfma_f32_16x16x32_bf16 v[18:21], v[176:179], v[208:211], v[18:21]
	v_mfma_f32_16x16x32_bf16 v[10:13], v[168:171], v[216:219], v[10:13]
	v_mfma_f32_16x16x32_bf16 v[2:5], v[176:179], v[216:219], v[2:5]
	v_mfma_f32_16x16x32_bf16 v[58:61], v[172:175], v[188:191], v[58:61]
	v_mfma_f32_16x16x32_bf16 v[50:53], v[180:183], v[188:191], v[50:53]
	v_mfma_f32_16x16x32_bf16 v[42:45], v[172:175], v[204:207], v[42:45]
	v_mfma_f32_16x16x32_bf16 v[34:37], v[180:183], v[204:207], v[34:37]
	v_mfma_f32_16x16x32_bf16 v[26:29], v[172:175], v[212:215], v[26:29]
	v_mfma_f32_16x16x32_bf16 v[18:21], v[180:183], v[212:215], v[18:21]
	v_mfma_f32_16x16x32_bf16 v[10:13], v[172:175], v[220:223], v[10:13]
	v_mfma_f32_16x16x32_bf16 v[2:5], v[180:183], v[220:223], v[2:5]
	s_barrier
	s_setprio 0
	s_cbranch_scc0 .Lrot_369
	s_and_b64 vcc, exec, s[6:7]
	s_cbranch_vccz .LBB0_372
	s_barrier

; #define PG8_STAGE(bufoff, gbase, voff) do { _Pragma("unroll") for (int _i = 0; _i < 2; ++_i) \
;         __builtin_amdgcn_global_load_lds((const gunsigned*)((const gchar*)(gbase) + (voff)[_i]), (LAS unsigned*)(lds + (bufoff) + ldsw + _i * 8192), 16, 0, 0); } while (0)
; #define PG8_LDA(dst, b, h) do { _Pragma("unroll") for (int m = 0; m < 4; ++m) _Pragma("unroll") for (int k = 0; k < 2; ++k) dst[m][k] = *(const LAS bf16x8*)(lds + PG8_SA(b, h) + aoff + m * 2048 + k * 1024); } while (0)
; #define PG8_LDB(dst, b, h) do { _Pragma("unroll") for (int n = 0; n < 2; ++n) _Pragma("unroll") for (int k = 0; k < 2; ++k) dst[n][k] = *(const LAS bf16x8*)(lds + PG8_SB(b, h) + boff + n * 2048 + k * 1024); } while (0)
; #define PG8_MMA(ai, bj, At, Bt) do { __builtin_amdgcn_s_setprio(1); _Pragma("unroll") for (int m = 0; m < 4; ++m) _Pragma("unroll") for (int n = 0; n < 2; ++n) _Pragma("unroll") for (int k = 0; k < 2; ++k) \
;         acc[ai][bj][m][n] = __builtin_amdgcn_mfma_f32_16x16x32_bf16(Bt[n][k], At[m][k], acc[ai][bj][m][n], 0, 0, 0); __builtin_amdgcn_s_setprio(0); } while (0)
; #define PG8_WAIT_V(n) asm volatile("s_waitcnt vmcnt(" #n ")" ::: "memory")
; #define PG8_WAIT_L(n) asm volatile("s_waitcnt lgkmcnt(" #n ")" ::: "memory")
; #define PG8_BAR __builtin_amdgcn_s_barrier()
; #define PG8_SCHED __builtin_amdgcn_sched_barrier(0)
; template <class Epi, class Sched>
; __device__ __forceinline__ void gemm_phase(LAS unsigned char* lds, const int tid, const Gemm g, const Sched& S, const Epi& E) {
;     ...
;         for (int t = 0; t < nt; t += 2) {
;             const bool last = (t == nt - 2);
;             const gchar* a1 = cA + (size_t)(t + 1) * kstep;
;             const gchar* a2 = last ? nA : cA + (size_t)(t + 2) * kstep; const gchar* b2 = last ? nB : cB + (size_t)(t + 2) * kstep;
;             const gchar* a3 = a2 + kstep; const gchar* b3 = b2 + kstep;
;             PG8_LDB(B0, 0, 0); PG8_LDB(B1, 0, 1); PG8_SCHED; PG8_LDA(At, 0, 0); PG8_STAGE(PG8_SA(1, 1), a1 + hstep, voffA);
;             PG8_WAIT_V(8); PG8_WAIT_L(0); PG8_BAR; PG8_MMA(0, 0, At, B0); PG8_MMA(0, 1, At, B1); PG8_BAR; PG8_SCHED;
;             PG8_LDA(At, 0, 1); PG8_STAGE(PG8_SB(0, 0), b2, voffB); PG8_STAGE(PG8_SB(0, 1), b2 + hstep, voffB); PG8_STAGE(PG8_SA(0, 0), a2, voffA);
;             PG8_WAIT_V(8); PG8_WAIT_L(0); PG8_BAR; PG8_MMA(1, 0, At, B0); PG8_MMA(1, 1, At, B1); PG8_BAR; PG8_SCHED;
.LBB0_397:
	s_add_u32 s20, s92, 0xfffc0080
	s_addc_u32 s21, s93, -1
	s_cmp_eq_u32 s53, 12
	s_cselect_b32 s73, s1, s21
	s_cselect_b32 s72, s31, s20
	s_cselect_b32 s21, s17, s52
	s_cselect_b32 s20, s50, s51
.Lrot_397:
	s_add_i32 s29, 0, 0x10000
	s_add_i32 s30, 0, 0x14000
	v_add_u32_e32 v142, s29, v177
	v_add_u32_e32 v168, s30, v177
	ds_read_b128 v[130:133], v142
	ds_read_b128 v[134:137], v142 offset:1024
	ds_read_b128 v[138:141], v142 offset:2048
	ds_read_b128 v[142:145], v142 offset:3072
	ds_read_b128 v[146:149], v168
	ds_read_b128 v[150:153], v168 offset:1024
	ds_read_b128 v[164:167], v168 offset:2048
	ds_read_b128 v[168:171], v168 offset:3072
	s_add_i32 m0, s43, 0xc000
	ds_read_b128 v[172:175], v181
	ds_read_b128 v[182:185], v181 offset:1024
	ds_read_b128 v[186:189], v181 offset:2048
	ds_read_b128 v[190:193], v181 offset:3072
	ds_read_b128 v[204:207], v181 offset:4096
	ds_read_b128 v[208:211], v181 offset:5120
	ds_read_b128 v[212:215], v181 offset:6144
	ds_read_b128 v[216:219], v181 offset:7168
	global_load_lds_dwordx4 v162, s[92:93]
	s_add_i32 m0, s43, 0xe000
	s_nop 0
	global_load_lds_dwordx4 v160, s[92:93]
	s_waitcnt vmcnt(8)
	s_waitcnt lgkmcnt(0)
	s_barrier
	s_setprio 1
	v_mfma_f32_16x16x32_bf16 v[126:129], v[130:133], v[172:175], v[126:129]
	v_mfma_f32_16x16x32_bf16 v[122:125], v[138:141], v[172:175], v[122:125]
	v_mfma_f32_16x16x32_bf16 v[110:113], v[130:133], v[186:189], v[110:113]
	v_mfma_f32_16x16x32_bf16 v[106:109], v[138:141], v[186:189], v[106:109]
	v_mfma_f32_16x16x32_bf16 v[94:97], v[130:133], v[204:207], v[94:97]
	v_mfma_f32_16x16x32_bf16 v[90:93], v[138:141], v[204:207], v[90:93]
	v_mfma_f32_16x16x32_bf16 v[78:81], v[130:133], v[212:215], v[78:81]
	v_mfma_f32_16x16x32_bf16 v[74:77], v[138:141], v[212:215], v[74:77]
	v_mfma_f32_16x16x32_bf16 v[126:129], v[134:137], v[182:185], v[126:129]
	v_mfma_f32_16x16x32_bf16 v[122:125], v[142:145], v[182:185], v[122:125]
	v_mfma_f32_16x16x32_bf16 v[110:113], v[134:137], v[190:193], v[110:113]
	v_mfma_f32_16x16x32_bf16 v[106:109], v[142:145], v[190:193], v[106:109]
	v_mfma_f32_16x16x32_bf16 v[94:97], v[134:137], v[208:211], v[94:97]
	v_mfma_f32_16x16x32_bf16 v[90:93], v[142:145], v[208:211], v[90:93]
	v_mfma_f32_16x16x32_bf16 v[78:81], v[134:137], v[216:219], v[78:81]
	v_mfma_f32_16x16x32_bf16 v[74:77], v[142:145], v[216:219], v[74:77]
	s_setprio 0
	s_setprio 1
	v_mfma_f32_16x16x32_bf16 v[118:121], v[146:149], v[172:175], v[118:121]
	v_mfma_f32_16x16x32_bf16 v[114:117], v[164:167], v[172:175], v[114:117]
	v_mfma_f32_16x16x32_bf16 v[102:105], v[146:149], v[186:189], v[102:105]
	v_mfma_f32_16x16x32_bf16 v[98:101], v[164:167], v[186:189], v[98:101]
	v_mfma_f32_16x16x32_bf16 v[86:89], v[146:149], v[204:207], v[86:89]
	v_mfma_f32_16x16x32_bf16 v[82:85], v[164:167], v[204:207], v[82:85]
	v_mfma_f32_16x16x32_bf16 v[70:73], v[146:149], v[212:215], v[70:73]
	v_mfma_f32_16x16x32_bf16 v[66:69], v[164:167], v[212:215], v[66:69]
	v_mfma_f32_16x16x32_bf16 v[118:121], v[150:153], v[182:185], v[118:121]
	v_mfma_f32_16x16x32_bf16 v[114:117], v[168:171], v[182:185], v[114:117]
	v_mfma_f32_16x16x32_bf16 v[102:105], v[150:153], v[190:193], v[102:105]
	v_mfma_f32_16x16x32_bf16 v[98:101], v[168:171], v[190:193], v[98:101]
	v_mfma_f32_16x16x32_bf16 v[86:89], v[150:153], v[208:211], v[86:89]
	v_mfma_f32_16x16x32_bf16 v[82:85], v[168:171], v[208:211], v[82:85]
	v_mfma_f32_16x16x32_bf16 v[70:73], v[150:153], v[216:219], v[70:73]
	v_mfma_f32_16x16x32_bf16 v[66:69], v[168:171], v[216:219], v[66:69]
	s_barrier
	s_setprio 0
	s_add_i32 s29, s29, s15
	s_mov_b32 m0, s29
	ds_read_b128 v[172:175], v181 offset:16384
	ds_read_b128 v[182:185], v181 offset:17408
	ds_read_b128 v[186:189], v181 offset:18432
	ds_read_b128 v[190:193], v181 offset:19456
	ds_read_b128 v[204:207], v181 offset:20480
	ds_read_b128 v[208:211], v181 offset:21504
	ds_read_b128 v[212:215], v181 offset:22528
	ds_read_b128 v[216:219], v181 offset:23552
	global_load_lds_dwordx4 v0, s[20:21]
	s_add_i32 m0, s29, 0x2000
	s_add_u32 s54, s20, 0x40000
	s_addc_u32 s55, s21, 0
	s_add_i32 s29, s30, s15
	global_load_lds_dwordx4 v158, s[20:21]
	s_mov_b32 m0, s29
	s_nop 0
	global_load_lds_dwordx4 v0, s[54:55]
	s_add_i32 m0, s29, 0x2000
	s_nop 0
	global_load_lds_dwordx4 v158, s[54:55]
	s_mov_b32 m0, s43
	s_nop 0
	global_load_lds_dwordx4 v154, s[72:73]
	s_mov_b32 m0, s44
	s_nop 0
	global_load_lds_dwordx4 v156, s[72:73]
	s_waitcnt vmcnt(8)
	s_waitcnt lgkmcnt(0)
	s_barrier
	s_setprio 1
	v_mfma_f32_16x16x32_bf16 v[62:65], v[130:133], v[172:175], v[62:65]
	v_mfma_f32_16x16x32_bf16 v[58:61], v[138:141], v[172:175], v[58:61]
	v_mfma_f32_16x16x32_bf16 v[46:49], v[130:133], v[186:189], v[46:49]
	v_mfma_f32_16x16x32_bf16 v[42:45], v[138:141], v[186:189], v[42:45]
	v_mfma_f32_16x16x32_bf16 v[30:33], v[130:133], v[204:207], v[30:33]
	v_mfma_f32_16x16x32_bf16 v[26:29], v[138:141], v[204:207], v[26:29]
	v_mfma_f32_16x16x32_bf16 v[14:17], v[130:133], v[212:215], v[14:17]
	v_mfma_f32_16x16x32_bf16 v[10:13], v[138:141], v[212:215], v[10:13]
	v_mfma_f32_16x16x32_bf16 v[62:65], v[134:137], v[182:185], v[62:65]
	v_mfma_f32_16x16x32_bf16 v[58:61], v[142:145], v[182:185], v[58:61]
	v_mfma_f32_16x16x32_bf16 v[46:49], v[134:137], v[190:193], v[46:49]
	v_mfma_f32_16x16x32_bf16 v[42:45], v[142:145], v[190:193], v[42:45]
	v_mfma_f32_16x16x32_bf16 v[30:33], v[134:137], v[208:211], v[30:33]
	v_mfma_f32_16x16x32_bf16 v[26:29], v[142:145], v[208:211], v[26:29]
	v_mfma_f32_16x16x32_bf16 v[14:17], v[134:137], v[216:219], v[14:17]
	v_mfma_f32_16x16x32_bf16 v[10:13], v[142:145], v[216:219], v[10:13]
	s_setprio 0
	s_setprio 1
	v_mfma_f32_16x16x32_bf16 v[54:57], v[146:149], v[172:175], v[54:57]
	v_mfma_f32_16x16x32_bf16 v[50:53], v[164:167], v[172:175], v[50:53]
	v_mfma_f32_16x16x32_bf16 v[38:41], v[146:149], v[186:189], v[38:41]
	v_mfma_f32_16x16x32_bf16 v[34:37], v[164:167], v[186:189], v[34:37]
	v_mfma_f32_16x16x32_bf16 v[22:25], v[146:149], v[204:207], v[22:25]
	v_mfma_f32_16x16x32_bf16 v[18:21], v[164:167], v[204:207], v[18:21]
	v_mfma_f32_16x16x32_bf16 v[6:9], v[146:149], v[212:215], v[6:9]
	v_mfma_f32_16x16x32_bf16 v[2:5], v[164:167], v[212:215], v[2:5]
	v_mfma_f32_16x16x32_bf16 v[54:57], v[150:153], v[182:185], v[54:57]
	v_mfma_f32_16x16x32_bf16 v[50:53], v[168:171], v[182:185], v[50:53]
	v_mfma_f32_16x16x32_bf16 v[38:41], v[150:153], v[190:193], v[38:41]
	v_mfma_f32_16x16x32_bf16 v[34:37], v[168:171], v[190:193], v[34:37]
	v_mfma_f32_16x16x32_bf16 v[22:25], v[150:153], v[208:211], v[22:25]
	v_mfma_f32_16x16x32_bf16 v[18:21], v[168:171], v[208:211], v[18:21]
	v_mfma_f32_16x16x32_bf16 v[6:9], v[150:153], v[216:219], v[6:9]
	v_mfma_f32_16x16x32_bf16 v[2:5], v[168:171], v[216:219], v[2:5]
	s_barrier
; #define PG8_STAGE(bufoff, gbase, voff) do { _Pragma("unroll") for (int _i = 0; _i < 2; ++_i) \
;         __builtin_amdgcn_global_load_lds((const gunsigned*)((const gchar*)(gbase) + (voff)[_i]), (LAS unsigned*)(lds + (bufoff) + ldsw + _i * 8192), 16, 0, 0); } while (0)
; #define PG8_LDA(dst, b, h) do { _Pragma("unroll") for (int m = 0; m < 4; ++m) _Pragma("unroll") for (int k = 0; k < 2; ++k) dst[m][k] = *(const LAS bf16x8*)(lds + PG8_SA(b, h) + aoff + m * 2048 + k * 1024); } while (0)
; #define PG8_LDB(dst, b, h) do { _Pragma("unroll") for (int n = 0; n < 2; ++n) _Pragma("unroll") for (int k = 0; k < 2; ++k) dst[n][k] = *(const LAS bf16x8*)(lds + PG8_SB(b, h) + boff + n * 2048 + k * 1024); } while (0)
; #define PG8_MMA(ai, bj, At, Bt) do { __builtin_amdgcn_s_setprio(1); _Pragma("unroll") for (int m = 0; m < 4; ++m) _Pragma("unroll") for (int n = 0; n < 2; ++n) _Pragma("unroll") for (int k = 0; k < 2; ++k) \
;         acc[ai][bj][m][n] = __builtin_amdgcn_mfma_f32_16x16x32_bf16(Bt[n][k], At[m][k], acc[ai][bj][m][n], 0, 0, 0); __builtin_amdgcn_s_setprio(0); } while (0)
; #define PG8_WAIT_V(n) asm volatile("s_waitcnt vmcnt(" #n ")" ::: "memory")
; #define PG8_WAIT_L(n) asm volatile("s_waitcnt lgkmcnt(" #n ")" ::: "memory")
; #define PG8_BAR __builtin_amdgcn_s_barrier()
; #define PG8_SCHED __builtin_amdgcn_sched_barrier(0)
; template <class Epi, class Sched>
; __device__ __forceinline__ void gemm_phase(LAS unsigned char* lds, const int tid, const Gemm g, const Sched& S, const Epi& E) {
;     ...
;             const bool last = (t == nt - 2);
;             const gchar* a1 = cA + (size_t)(t + 1) * kstep;
;             const gchar* a2 = last ? nA : cA + (size_t)(t + 2) * kstep; const gchar* b2 = last ? nB : cB + (size_t)(t + 2) * kstep;
;             const gchar* a3 = a2 + kstep; const gchar* b3 = b2 + kstep;
;     ...
;             PG8_LDB(B0, 1, 0); PG8_LDB(B1, 1, 1); PG8_SCHED; PG8_LDA(At, 1, 0); PG8_STAGE(PG8_SA(0, 1), a2 + hstep, voffA);
;             PG8_WAIT_V(8); PG8_WAIT_L(0); PG8_BAR; PG8_MMA(0, 0, At, B0); PG8_MMA(0, 1, At, B1); PG8_BAR; PG8_SCHED;
;             PG8_LDA(At, 1, 1); PG8_STAGE(PG8_SB(1, 0), b3, voffB); PG8_STAGE(PG8_SB(1, 1), b3 + hstep, voffB); PG8_STAGE(PG8_SA(1, 0), a3, voffA);
;             PG8_WAIT_V(8); PG8_WAIT_L(0); PG8_BAR; PG8_MMA(1, 0, At, B0); PG8_MMA(1, 1, At, B1); PG8_BAR; PG8_SCHED;
	s_setprio 0
	s_add_i32 s29, 0, 0x18000
	s_add_i32 s30, 0, 0x1c000
	v_add_u32_e32 v142, s29, v177
	v_add_u32_e32 v168, s30, v177
	ds_read_b128 v[130:133], v142
	ds_read_b128 v[134:137], v142 offset:1024
	ds_read_b128 v[138:141], v142 offset:2048
	ds_read_b128 v[142:145], v142 offset:3072
	ds_read_b128 v[146:149], v168
	ds_read_b128 v[150:153], v168 offset:1024
	ds_read_b128 v[164:167], v168 offset:2048
	ds_read_b128 v[168:171], v168 offset:3072
	s_add_u32 s54, s72, 0x40000
	s_addc_u32 s55, s73, 0
	s_mov_b32 m0, s45
	ds_read_b128 v[172:175], v181 offset:32768
	ds_read_b128 v[182:185], v181 offset:33792
	ds_read_b128 v[186:189], v181 offset:34816
	ds_read_b128 v[190:193], v181 offset:35840
	ds_read_b128 v[204:207], v181 offset:36864
	ds_read_b128 v[208:211], v181 offset:37888
	ds_read_b128 v[212:215], v181 offset:38912
	ds_read_b128 v[216:219], v181 offset:39936
	global_load_lds_dwordx4 v154, s[54:55]
	s_mov_b32 m0, s46
	s_nop 0
	global_load_lds_dwordx4 v156, s[54:55]
	s_waitcnt vmcnt(8)
	s_waitcnt lgkmcnt(0)
	s_barrier
	s_setprio 1
	v_mfma_f32_16x16x32_bf16 v[126:129], v[130:133], v[172:175], v[126:129]
	v_mfma_f32_16x16x32_bf16 v[122:125], v[138:141], v[172:175], v[122:125]
	v_mfma_f32_16x16x32_bf16 v[110:113], v[130:133], v[186:189], v[110:113]
	v_mfma_f32_16x16x32_bf16 v[106:109], v[138:141], v[186:189], v[106:109]
	v_mfma_f32_16x16x32_bf16 v[94:97], v[130:133], v[204:207], v[94:97]
	v_mfma_f32_16x16x32_bf16 v[90:93], v[138:141], v[204:207], v[90:93]
	v_mfma_f32_16x16x32_bf16 v[78:81], v[130:133], v[212:215], v[78:81]
	v_mfma_f32_16x16x32_bf16 v[74:77], v[138:141], v[212:215], v[74:77]
	v_mfma_f32_16x16x32_bf16 v[126:129], v[134:137], v[182:185], v[126:129]
	v_mfma_f32_16x16x32_bf16 v[122:125], v[142:145], v[182:185], v[122:125]
	v_mfma_f32_16x16x32_bf16 v[110:113], v[134:137], v[190:193], v[110:113]
	v_mfma_f32_16x16x32_bf16 v[106:109], v[142:145], v[190:193], v[106:109]
	v_mfma_f32_16x16x32_bf16 v[94:97], v[134:137], v[208:211], v[94:97]
	v_mfma_f32_16x16x32_bf16 v[90:93], v[142:145], v[208:211], v[90:93]
	v_mfma_f32_16x16x32_bf16 v[78:81], v[134:137], v[216:219], v[78:81]
	v_mfma_f32_16x16x32_bf16 v[74:77], v[142:145], v[216:219], v[74:77]
	s_setprio 0
	s_setprio 1
	v_mfma_f32_16x16x32_bf16 v[118:121], v[146:149], v[172:175], v[118:121]
	v_mfma_f32_16x16x32_bf16 v[114:117], v[164:167], v[172:175], v[114:117]
	v_mfma_f32_16x16x32_bf16 v[102:105], v[146:149], v[186:189], v[102:105]
	v_mfma_f32_16x16x32_bf16 v[98:101], v[164:167], v[186:189], v[98:101]
	v_mfma_f32_16x16x32_bf16 v[86:89], v[146:149], v[204:207], v[86:89]
	v_mfma_f32_16x16x32_bf16 v[82:85], v[164:167], v[204:207], v[82:85]
	v_mfma_f32_16x16x32_bf16 v[70:73], v[146:149], v[212:215], v[70:73]
	v_mfma_f32_16x16x32_bf16 v[66:69], v[164:167], v[212:215], v[66:69]
	v_mfma_f32_16x16x32_bf16 v[118:121], v[150:153], v[182:185], v[118:121]
	v_mfma_f32_16x16x32_bf16 v[114:117], v[168:171], v[182:185], v[114:117]
	v_mfma_f32_16x16x32_bf16 v[102:105], v[150:153], v[190:193], v[102:105]
	v_mfma_f32_16x16x32_bf16 v[98:101], v[168:171], v[190:193], v[98:101]
	v_mfma_f32_16x16x32_bf16 v[86:89], v[150:153], v[208:211], v[86:89]
	v_mfma_f32_16x16x32_bf16 v[82:85], v[168:171], v[208:211], v[82:85]
	v_mfma_f32_16x16x32_bf16 v[70:73], v[150:153], v[216:219], v[70:73]
	v_mfma_f32_16x16x32_bf16 v[66:69], v[168:171], v[216:219], v[66:69]
	s_barrier
	s_setprio 0
	s_add_i32 s29, s29, s15
	s_mov_b32 m0, s29
	ds_read_b128 v[172:175], v181 offset:49152
	ds_read_b128 v[182:185], v181 offset:50176
	ds_read_b128 v[186:189], v181 offset:51200
	ds_read_b128 v[190:193], v181 offset:52224
	ds_read_b128 v[204:207], v181 offset:53248
	ds_read_b128 v[208:211], v181 offset:54272
	ds_read_b128 v[212:215], v181 offset:55296
	ds_read_b128 v[216:219], v181 offset:56320
	global_load_lds_dwordx4 v195, s[20:21]
	s_add_i32 m0, s29, 0x2000
	s_add_i32 s29, s30, s15
	global_load_lds_dwordx4 v201, s[20:21]
	s_add_u32 s20, s20, 0x40080
	s_addc_u32 s21, s21, 0
	s_mov_b32 m0, s29
	s_nop 0
	global_load_lds_dwordx4 v0, s[20:21]
	s_add_i32 m0, s29, 0x2000
	s_nop 0
	global_load_lds_dwordx4 v158, s[20:21]
	s_mov_b32 m0, s12
	s_nop 0
	global_load_lds_dwordx4 v221, s[72:73]
	s_mov_b32 m0, s47
	s_nop 0
	global_load_lds_dwordx4 v223, s[72:73]
	s_waitcnt vmcnt(8)
	s_waitcnt lgkmcnt(0)
	s_barrier
	s_setprio 1
	v_mfma_f32_16x16x32_bf16 v[62:65], v[130:133], v[172:175], v[62:65]
	v_mfma_f32_16x16x32_bf16 v[58:61], v[138:141], v[172:175], v[58:61]
	v_mfma_f32_16x16x32_bf16 v[46:49], v[130:133], v[186:189], v[46:49]
	v_mfma_f32_16x16x32_bf16 v[42:45], v[138:141], v[186:189], v[42:45]
	v_mfma_f32_16x16x32_bf16 v[30:33], v[130:133], v[204:207], v[30:33]
	v_mfma_f32_16x16x32_bf16 v[26:29], v[138:141], v[204:207], v[26:29]
	v_mfma_f32_16x16x32_bf16 v[14:17], v[130:133], v[212:215], v[14:17]
	v_mfma_f32_16x16x32_bf16 v[10:13], v[138:141], v[212:215], v[10:13]
	v_mfma_f32_16x16x32_bf16 v[62:65], v[134:137], v[182:185], v[62:65]
	v_mfma_f32_16x16x32_bf16 v[58:61], v[142:145], v[182:185], v[58:61]
	v_mfma_f32_16x16x32_bf16 v[46:49], v[134:137], v[190:193], v[46:49]
	v_mfma_f32_16x16x32_bf16 v[42:45], v[142:145], v[190:193], v[42:45]
	v_mfma_f32_16x16x32_bf16 v[30:33], v[134:137], v[208:211], v[30:33]
	v_mfma_f32_16x16x32_bf16 v[26:29], v[142:145], v[208:211], v[26:29]
	v_mfma_f32_16x16x32_bf16 v[14:17], v[134:137], v[216:219], v[14:17]
	v_mfma_f32_16x16x32_bf16 v[10:13], v[142:145], v[216:219], v[10:13]
	s_setprio 0
	s_setprio 1
	s_add_i32 s53, s53, 2
	s_add_u32 s51, s51, 0x100
	s_addc_u32 s52, s52, 0
	s_add_u32 s92, s92, 0x100
	s_addc_u32 s93, s93, 0
	s_cmp_gt_u32 s53, 13
	s_cbranch_scc1 .Lrot_skip_397
	s_add_u32 s20, s92, 0xfffc0080
	s_addc_u32 s21, s93, -1
	s_cmp_eq_u32 s53, 12
	s_cselect_b32 s73, s1, s21
	s_cselect_b32 s72, s31, s20
	s_cselect_b32 s21, s17, s52
	s_cselect_b32 s20, s50, s51
.Lrot_skip_397:
	s_cmp_gt_u32 s53, 13
	v_mfma_f32_16x16x32_bf16 v[54:57], v[146:149], v[172:175], v[54:57]
	v_mfma_f32_16x16x32_bf16 v[50:53], v[164:167], v[172:175], v[50:53]
	v_mfma_f32_16x16x32_bf16 v[38:41], v[146:149], v[186:189], v[38:41]
	v_mfma_f32_16x16x32_bf16 v[34:37], v[164:167], v[186:189], v[34:37]
	v_mfma_f32_16x16x32_bf16 v[22:25], v[146:149], v[204:207], v[22:25]
	v_mfma_f32_16x16x32_bf16 v[18:21], v[164:167], v[204:207], v[18:21]
	v_mfma_f32_16x16x32_bf16 v[6:9], v[146:149], v[212:215], v[6:9]
	v_mfma_f32_16x16x32_bf16 v[2:5], v[164:167], v[212:215], v[2:5]
	v_mfma_f32_16x16x32_bf16 v[54:57], v[150:153], v[182:185], v[54:57]
	v_mfma_f32_16x16x32_bf16 v[50:53], v[168:171], v[182:185], v[50:53]
	v_mfma_f32_16x16x32_bf16 v[38:41], v[150:153], v[190:193], v[38:41]
	v_mfma_f32_16x16x32_bf16 v[34:37], v[168:171], v[190:193], v[34:37]
	v_mfma_f32_16x16x32_bf16 v[22:25], v[150:153], v[208:211], v[22:25]
	v_mfma_f32_16x16x32_bf16 v[18:21], v[168:171], v[208:211], v[18:21]
	v_mfma_f32_16x16x32_bf16 v[6:9], v[150:153], v[216:219], v[6:9]
	v_mfma_f32_16x16x32_bf16 v[2:5], v[168:171], v[216:219], v[2:5]
	s_barrier
	s_setprio 0
	s_cbranch_scc0 .Lrot_397
	s_and_b64 vcc, exec, s[10:11]
	s_cbranch_vccz .LBB0_400
	s_barrier

; #define PG8_STAGE(bufoff, gbase, voff) do { _Pragma("unroll") for (int _i = 0; _i < 2; ++_i) \
;         __builtin_amdgcn_global_load_lds((const gunsigned*)((const gchar*)(gbase) + (voff)[_i]), (LAS unsigned*)(lds + (bufoff) + ldsw + _i * 8192), 16, 0, 0); } while (0)
; #define PG8_LDA(dst, b, h) do { _Pragma("unroll") for (int m = 0; m < 4; ++m) _Pragma("unroll") for (int k = 0; k < 2; ++k) dst[m][k] = *(const LAS bf16x8*)(lds + PG8_SA(b, h) + aoff + m * 2048 + k * 1024); } while (0)
; #define PG8_LDB(dst, b, h) do { _Pragma("unroll") for (int n = 0; n < 2; ++n) _Pragma("unroll") for (int k = 0; k < 2; ++k) dst[n][k] = *(const LAS bf16x8*)(lds + PG8_SB(b, h) + boff + n * 2048 + k * 1024); } while (0)
; #define PG8_MMA(ai, bj, At, Bt) do { __builtin_amdgcn_s_setprio(1); _Pragma("unroll") for (int m = 0; m < 4; ++m) _Pragma("unroll") for (int n = 0; n < 2; ++n) _Pragma("unroll") for (int k = 0; k < 2; ++k) \
;         acc[ai][bj][m][n] = __builtin_amdgcn_mfma_f32_16x16x32_bf16(Bt[n][k], At[m][k], acc[ai][bj][m][n], 0, 0, 0); __builtin_amdgcn_s_setprio(0); } while (0)
; #define PG8_WAIT_V(n) asm volatile("s_waitcnt vmcnt(" #n ")" ::: "memory")
; #define PG8_WAIT_L(n) asm volatile("s_waitcnt lgkmcnt(" #n ")" ::: "memory")
; #define PG8_BAR __builtin_amdgcn_s_barrier()
; #define PG8_SCHED __builtin_amdgcn_sched_barrier(0)
; template <class Epi, class Sched>
; __device__ __forceinline__ void gemm_phase(LAS unsigned char* lds, const int tid, const Gemm g, const Sched& S, const Epi& E) {
;     ...
;         for (int t = 0; t < nt; t += 2) {
;             const bool last = (t == nt - 2);
;             const gchar* a1 = cA + (size_t)(t + 1) * kstep;
;             const gchar* a2 = last ? nA : cA + (size_t)(t + 2) * kstep; const gchar* b2 = last ? nB : cB + (size_t)(t + 2) * kstep;
;             const gchar* a3 = a2 + kstep; const gchar* b3 = b2 + kstep;
;             PG8_LDB(B0, 0, 0); PG8_LDB(B1, 0, 1); PG8_SCHED; PG8_LDA(At, 0, 0); PG8_STAGE(PG8_SA(1, 1), a1 + hstep, voffA);
;             PG8_WAIT_V(8); PG8_WAIT_L(0); PG8_BAR; PG8_MMA(0, 0, At, B0); PG8_MMA(0, 1, At, B1); PG8_BAR; PG8_SCHED;
;             PG8_LDA(At, 0, 1); PG8_STAGE(PG8_SB(0, 0), b2, voffB); PG8_STAGE(PG8_SB(0, 1), b2 + hstep, voffB); PG8_STAGE(PG8_SA(0, 0), a2, voffA);
;             PG8_WAIT_V(8); PG8_WAIT_L(0); PG8_BAR; PG8_MMA(1, 0, At, B0); PG8_MMA(1, 1, At, B1); PG8_BAR; PG8_SCHED;
.LBB0_444:
	s_add_u32 s20, s16, 0xfffe0080
	s_addc_u32 s21, s17, -1
	s_cmp_eq_u32 s51, 4
	s_cselect_b32 s73, s1, s21
	s_cselect_b32 s72, s5, s20
	s_cselect_b32 s21, s15, s31
	s_cselect_b32 s20, s23, s24
.Lrot_444:
	s_add_i32 s29, 0, 0x10000
	v_add_u32_e32 v122, s29, v242
	s_add_i32 s30, 0, 0x14000
	ds_read_b128 v[132:135], v122
	ds_read_b128 v[136:139], v122 offset:1024
	ds_read_b128 v[140:143], v122 offset:2048
	ds_read_b128 v[144:147], v122 offset:3072
	v_add_u32_e32 v122, s30, v242
	ds_read_b128 v[148:151], v122
	ds_read_b128 v[152:155], v122 offset:1024
	ds_read_b128 v[156:159], v122 offset:2048
	ds_read_b128 v[160:163], v122 offset:3072
	s_add_i32 m0, s93, 0xc000
	ds_read_b128 v[164:167], v244
	ds_read_b128 v[168:171], v244 offset:1024
	ds_read_b128 v[172:175], v244 offset:2048
	ds_read_b128 v[176:179], v244 offset:3072
	ds_read_b128 v[180:183], v244 offset:4096
	ds_read_b128 v[184:187], v244 offset:5120
	ds_read_b128 v[188:191], v244 offset:6144
	ds_read_b128 v[192:195], v244 offset:7168
	global_load_lds_dwordx4 v212, s[16:17]
	s_add_i32 m0, s93, 0xe000
	s_nop 0
	global_load_lds_dwordx4 v210, s[16:17]
	s_waitcnt vmcnt(8)
	s_waitcnt lgkmcnt(0)
	s_barrier
	s_setprio 1
	v_mfma_f32_16x16x32_bf16 v[128:131], v[132:135], v[164:167], v[128:131]
	v_mfma_f32_16x16x32_bf16 v[122:125], v[140:143], v[164:167], v[124:127]
	v_mfma_f32_16x16x32_bf16 v[110:113], v[132:135], v[172:175], v[110:113]
	v_mfma_f32_16x16x32_bf16 v[106:109], v[140:143], v[172:175], v[106:109]
	v_mfma_f32_16x16x32_bf16 v[94:97], v[132:135], v[180:183], v[94:97]
	v_mfma_f32_16x16x32_bf16 v[90:93], v[140:143], v[180:183], v[90:93]
	v_mfma_f32_16x16x32_bf16 v[78:81], v[132:135], v[188:191], v[78:81]
	v_mfma_f32_16x16x32_bf16 v[74:77], v[140:143], v[188:191], v[74:77]
	v_mfma_f32_16x16x32_bf16 v[128:131], v[136:139], v[168:171], v[128:131]
	v_mfma_f32_16x16x32_bf16 v[122:125], v[144:147], v[168:171], v[122:125]
	v_mfma_f32_16x16x32_bf16 v[110:113], v[136:139], v[176:179], v[110:113]
	v_mfma_f32_16x16x32_bf16 v[106:109], v[144:147], v[176:179], v[106:109]
	v_mfma_f32_16x16x32_bf16 v[94:97], v[136:139], v[184:187], v[94:97]
	v_mfma_f32_16x16x32_bf16 v[90:93], v[144:147], v[184:187], v[90:93]
	v_mfma_f32_16x16x32_bf16 v[78:81], v[136:139], v[192:195], v[78:81]
	v_mfma_f32_16x16x32_bf16 v[74:77], v[144:147], v[192:195], v[74:77]
	s_setprio 0
	s_setprio 1
	v_mfma_f32_16x16x32_bf16 v[118:121], v[148:151], v[164:167], v[118:121]
	v_mfma_f32_16x16x32_bf16 v[114:117], v[156:159], v[164:167], v[114:117]
	v_mfma_f32_16x16x32_bf16 v[102:105], v[148:151], v[172:175], v[102:105]
	v_mfma_f32_16x16x32_bf16 v[98:101], v[156:159], v[172:175], v[98:101]
	v_mfma_f32_16x16x32_bf16 v[86:89], v[148:151], v[180:183], v[86:89]
	v_mfma_f32_16x16x32_bf16 v[82:85], v[156:159], v[180:183], v[82:85]
	v_mfma_f32_16x16x32_bf16 v[70:73], v[148:151], v[188:191], v[70:73]
	v_mfma_f32_16x16x32_bf16 v[66:69], v[156:159], v[188:191], v[66:69]
	v_mfma_f32_16x16x32_bf16 v[118:121], v[152:155], v[168:171], v[118:121]
	v_mfma_f32_16x16x32_bf16 v[114:117], v[160:163], v[168:171], v[114:117]
	v_mfma_f32_16x16x32_bf16 v[102:105], v[152:155], v[176:179], v[102:105]
	v_mfma_f32_16x16x32_bf16 v[98:101], v[160:163], v[176:179], v[98:101]
	v_mfma_f32_16x16x32_bf16 v[86:89], v[152:155], v[184:187], v[86:89]
	v_mfma_f32_16x16x32_bf16 v[82:85], v[160:163], v[184:187], v[82:85]
	v_mfma_f32_16x16x32_bf16 v[70:73], v[152:155], v[192:195], v[70:73]
	v_mfma_f32_16x16x32_bf16 v[66:69], v[160:163], v[192:195], v[66:69]
	s_barrier
	s_setprio 0
	s_add_i32 s29, s29, s42
	s_mov_b32 m0, s29
	ds_read_b128 v[164:167], v244 offset:16384
	ds_read_b128 v[168:171], v244 offset:17408
	ds_read_b128 v[172:175], v244 offset:18432
	ds_read_b128 v[176:179], v244 offset:19456
	ds_read_b128 v[180:183], v244 offset:20480
	ds_read_b128 v[184:187], v244 offset:21504
	ds_read_b128 v[188:191], v244 offset:22528
	ds_read_b128 v[192:195], v244 offset:23552
	global_load_lds_dwordx4 v0, s[20:21]
	s_add_i32 m0, s29, 0x2000
	s_add_u32 s52, s20, 0x20000
	s_addc_u32 s53, s21, 0
	s_add_i32 s29, s30, s42
	global_load_lds_dwordx4 v208, s[20:21]
	s_mov_b32 m0, s29
	s_nop 0
	global_load_lds_dwordx4 v0, s[52:53]
	s_add_i32 m0, s29, 0x2000
	s_nop 0
	global_load_lds_dwordx4 v208, s[52:53]
	s_mov_b32 m0, s93
	s_nop 0
	global_load_lds_dwordx4 v204, s[72:73]
	s_mov_b32 m0, s44
	s_nop 0
	global_load_lds_dwordx4 v206, s[72:73]
	s_waitcnt vmcnt(8)
	s_waitcnt lgkmcnt(0)
	s_barrier
	s_setprio 1
	v_mfma_f32_16x16x32_bf16 v[62:65], v[132:135], v[164:167], v[62:65]
	v_mfma_f32_16x16x32_bf16 v[58:61], v[140:143], v[164:167], v[58:61]
	v_mfma_f32_16x16x32_bf16 v[46:49], v[132:135], v[172:175], v[46:49]
	v_mfma_f32_16x16x32_bf16 v[42:45], v[140:143], v[172:175], v[42:45]
	v_mfma_f32_16x16x32_bf16 v[30:33], v[132:135], v[180:183], v[30:33]
	v_mfma_f32_16x16x32_bf16 v[26:29], v[140:143], v[180:183], v[26:29]
	v_mfma_f32_16x16x32_bf16 v[14:17], v[132:135], v[188:191], v[14:17]
	v_mfma_f32_16x16x32_bf16 v[10:13], v[140:143], v[188:191], v[10:13]
	v_mfma_f32_16x16x32_bf16 v[62:65], v[136:139], v[168:171], v[62:65]
	v_mfma_f32_16x16x32_bf16 v[58:61], v[144:147], v[168:171], v[58:61]
	v_mfma_f32_16x16x32_bf16 v[46:49], v[136:139], v[176:179], v[46:49]
	v_mfma_f32_16x16x32_bf16 v[42:45], v[144:147], v[176:179], v[42:45]
	v_mfma_f32_16x16x32_bf16 v[30:33], v[136:139], v[184:187], v[30:33]
	v_mfma_f32_16x16x32_bf16 v[26:29], v[144:147], v[184:187], v[26:29]
	v_mfma_f32_16x16x32_bf16 v[14:17], v[136:139], v[192:195], v[14:17]
	v_mfma_f32_16x16x32_bf16 v[10:13], v[144:147], v[192:195], v[10:13]
	s_setprio 0
	s_setprio 1
	v_mfma_f32_16x16x32_bf16 v[54:57], v[148:151], v[164:167], v[54:57]
	v_mfma_f32_16x16x32_bf16 v[50:53], v[156:159], v[164:167], v[50:53]
	v_mfma_f32_16x16x32_bf16 v[38:41], v[148:151], v[172:175], v[38:41]
	v_mfma_f32_16x16x32_bf16 v[34:37], v[156:159], v[172:175], v[34:37]
	v_mfma_f32_16x16x32_bf16 v[22:25], v[148:151], v[180:183], v[22:25]
	v_mfma_f32_16x16x32_bf16 v[18:21], v[156:159], v[180:183], v[18:21]
	v_mfma_f32_16x16x32_bf16 v[6:9], v[148:151], v[188:191], v[6:9]
	v_mfma_f32_16x16x32_bf16 v[2:5], v[156:159], v[188:191], v[2:5]
	v_mfma_f32_16x16x32_bf16 v[54:57], v[152:155], v[168:171], v[54:57]
	v_mfma_f32_16x16x32_bf16 v[50:53], v[160:163], v[168:171], v[50:53]
	v_mfma_f32_16x16x32_bf16 v[38:41], v[152:155], v[176:179], v[38:41]
	v_mfma_f32_16x16x32_bf16 v[34:37], v[160:163], v[176:179], v[34:37]
	v_mfma_f32_16x16x32_bf16 v[22:25], v[152:155], v[184:187], v[22:25]
	v_mfma_f32_16x16x32_bf16 v[18:21], v[160:163], v[184:187], v[18:21]
	v_mfma_f32_16x16x32_bf16 v[6:9], v[152:155], v[192:195], v[6:9]
	v_mfma_f32_16x16x32_bf16 v[2:5], v[160:163], v[192:195], v[2:5]
	s_barrier
; #define PG8_STAGE(bufoff, gbase, voff) do { _Pragma("unroll") for (int _i = 0; _i < 2; ++_i) \
;         __builtin_amdgcn_global_load_lds((const gunsigned*)((const gchar*)(gbase) + (voff)[_i]), (LAS unsigned*)(lds + (bufoff) + ldsw + _i * 8192), 16, 0, 0); } while (0)
; #define PG8_LDA(dst, b, h) do { _Pragma("unroll") for (int m = 0; m < 4; ++m) _Pragma("unroll") for (int k = 0; k < 2; ++k) dst[m][k] = *(const LAS bf16x8*)(lds + PG8_SA(b, h) + aoff + m * 2048 + k * 1024); } while (0)
; #define PG8_LDB(dst, b, h) do { _Pragma("unroll") for (int n = 0; n < 2; ++n) _Pragma("unroll") for (int k = 0; k < 2; ++k) dst[n][k] = *(const LAS bf16x8*)(lds + PG8_SB(b, h) + boff + n * 2048 + k * 1024); } while (0)
; #define PG8_MMA(ai, bj, At, Bt) do { __builtin_amdgcn_s_setprio(1); _Pragma("unroll") for (int m = 0; m < 4; ++m) _Pragma("unroll") for (int n = 0; n < 2; ++n) _Pragma("unroll") for (int k = 0; k < 2; ++k) \
;         acc[ai][bj][m][n] = __builtin_amdgcn_mfma_f32_16x16x32_bf16(Bt[n][k], At[m][k], acc[ai][bj][m][n], 0, 0, 0); __builtin_amdgcn_s_setprio(0); } while (0)
; #define PG8_WAIT_V(n) asm volatile("s_waitcnt vmcnt(" #n ")" ::: "memory")
; #define PG8_WAIT_L(n) asm volatile("s_waitcnt lgkmcnt(" #n ")" ::: "memory")
; #define PG8_BAR __builtin_amdgcn_s_barrier()
; #define PG8_SCHED __builtin_amdgcn_sched_barrier(0)
; template <class Epi, class Sched>
; __device__ __forceinline__ void gemm_phase(LAS unsigned char* lds, const int tid, const Gemm g, const Sched& S, const Epi& E) {
;     ...
;             const bool last = (t == nt - 2);
;             const gchar* a1 = cA + (size_t)(t + 1) * kstep;
;             const gchar* a2 = last ? nA : cA + (size_t)(t + 2) * kstep; const gchar* b2 = last ? nB : cB + (size_t)(t + 2) * kstep;
;             const gchar* a3 = a2 + kstep; const gchar* b3 = b2 + kstep;
;     ...
;             PG8_LDB(B0, 1, 0); PG8_LDB(B1, 1, 1); PG8_SCHED; PG8_LDA(At, 1, 0); PG8_STAGE(PG8_SA(0, 1), a2 + hstep, voffA);
;             PG8_WAIT_V(8); PG8_WAIT_L(0); PG8_BAR; PG8_MMA(0, 0, At, B0); PG8_MMA(0, 1, At, B1); PG8_BAR; PG8_SCHED;
;             PG8_LDA(At, 1, 1); PG8_STAGE(PG8_SB(1, 0), b3, voffB); PG8_STAGE(PG8_SB(1, 1), b3 + hstep, voffB); PG8_STAGE(PG8_SA(1, 0), a3, voffA);
;             PG8_WAIT_V(8); PG8_WAIT_L(0); PG8_BAR; PG8_MMA(1, 0, At, B0); PG8_MMA(1, 1, At, B1); PG8_BAR; PG8_SCHED;
	s_setprio 0
	s_add_i32 s29, 0, 0x18000
	v_add_u32_e32 v126, s29, v242
	s_add_i32 s30, 0, 0x1c000
	ds_read_b128 v[132:135], v126
	ds_read_b128 v[136:139], v126 offset:1024
	ds_read_b128 v[140:143], v126 offset:2048
	ds_read_b128 v[144:147], v126 offset:3072
	v_add_u32_e32 v126, s30, v242
	ds_read_b128 v[148:151], v126
	ds_read_b128 v[152:155], v126 offset:1024
	ds_read_b128 v[156:159], v126 offset:2048
	ds_read_b128 v[160:163], v126 offset:3072
	s_add_u32 s52, s72, 0x20000
	s_addc_u32 s53, s73, 0
	s_mov_b32 m0, s45
	ds_read_b128 v[164:167], v244 offset:32768
	ds_read_b128 v[168:171], v244 offset:33792
	ds_read_b128 v[172:175], v244 offset:34816
	ds_read_b128 v[176:179], v244 offset:35840
	ds_read_b128 v[180:183], v244 offset:36864
	ds_read_b128 v[184:187], v244 offset:37888
	ds_read_b128 v[188:191], v244 offset:38912
	ds_read_b128 v[192:195], v244 offset:39936
	global_load_lds_dwordx4 v204, s[52:53]
	s_mov_b32 m0, s46
	s_nop 0
	global_load_lds_dwordx4 v206, s[52:53]
	s_waitcnt vmcnt(8)
	s_waitcnt lgkmcnt(0)
	s_barrier
	s_setprio 1
	v_mfma_f32_16x16x32_bf16 v[126:129], v[132:135], v[164:167], v[128:131]
	v_mfma_f32_16x16x32_bf16 v[122:125], v[140:143], v[164:167], v[122:125]
	v_mfma_f32_16x16x32_bf16 v[110:113], v[132:135], v[172:175], v[110:113]
	v_mfma_f32_16x16x32_bf16 v[106:109], v[140:143], v[172:175], v[106:109]
	v_mfma_f32_16x16x32_bf16 v[94:97], v[132:135], v[180:183], v[94:97]
	v_mfma_f32_16x16x32_bf16 v[90:93], v[140:143], v[180:183], v[90:93]
	v_mfma_f32_16x16x32_bf16 v[78:81], v[132:135], v[188:191], v[78:81]
	v_mfma_f32_16x16x32_bf16 v[74:77], v[140:143], v[188:191], v[74:77]
	v_mfma_f32_16x16x32_bf16 v[128:131], v[136:139], v[168:171], v[126:129]
	v_mfma_f32_16x16x32_bf16 v[124:127], v[144:147], v[168:171], v[122:125]
	v_mfma_f32_16x16x32_bf16 v[110:113], v[136:139], v[176:179], v[110:113]
	v_mfma_f32_16x16x32_bf16 v[106:109], v[144:147], v[176:179], v[106:109]
	v_mfma_f32_16x16x32_bf16 v[94:97], v[136:139], v[184:187], v[94:97]
	v_mfma_f32_16x16x32_bf16 v[90:93], v[144:147], v[184:187], v[90:93]
	v_mfma_f32_16x16x32_bf16 v[78:81], v[136:139], v[192:195], v[78:81]
	v_mfma_f32_16x16x32_bf16 v[74:77], v[144:147], v[192:195], v[74:77]
	s_setprio 0
	s_setprio 1
	v_mfma_f32_16x16x32_bf16 v[118:121], v[148:151], v[164:167], v[118:121]
	v_mfma_f32_16x16x32_bf16 v[114:117], v[156:159], v[164:167], v[114:117]
	v_mfma_f32_16x16x32_bf16 v[102:105], v[148:151], v[172:175], v[102:105]
	v_mfma_f32_16x16x32_bf16 v[98:101], v[156:159], v[172:175], v[98:101]
	v_mfma_f32_16x16x32_bf16 v[86:89], v[148:151], v[180:183], v[86:89]
	v_mfma_f32_16x16x32_bf16 v[82:85], v[156:159], v[180:183], v[82:85]
	v_mfma_f32_16x16x32_bf16 v[70:73], v[148:151], v[188:191], v[70:73]
	v_mfma_f32_16x16x32_bf16 v[66:69], v[156:159], v[188:191], v[66:69]
	v_mfma_f32_16x16x32_bf16 v[118:121], v[152:155], v[168:171], v[118:121]
	v_mfma_f32_16x16x32_bf16 v[114:117], v[160:163], v[168:171], v[114:117]
	v_mfma_f32_16x16x32_bf16 v[102:105], v[152:155], v[176:179], v[102:105]
	v_mfma_f32_16x16x32_bf16 v[98:101], v[160:163], v[176:179], v[98:101]
	v_mfma_f32_16x16x32_bf16 v[86:89], v[152:155], v[184:187], v[86:89]
	v_mfma_f32_16x16x32_bf16 v[82:85], v[160:163], v[184:187], v[82:85]
	v_mfma_f32_16x16x32_bf16 v[70:73], v[152:155], v[192:195], v[70:73]
	v_mfma_f32_16x16x32_bf16 v[66:69], v[160:163], v[192:195], v[66:69]
	s_barrier
	s_setprio 0
	s_add_i32 s29, s29, s42
	s_mov_b32 m0, s29
	ds_read_b128 v[164:167], v244 offset:49152
	ds_read_b128 v[168:171], v244 offset:50176
	ds_read_b128 v[172:175], v244 offset:51200
	ds_read_b128 v[176:179], v244 offset:52224
	ds_read_b128 v[180:183], v244 offset:53248
	ds_read_b128 v[184:187], v244 offset:54272
	ds_read_b128 v[188:191], v244 offset:55296
	ds_read_b128 v[192:195], v244 offset:56320
	global_load_lds_dwordx4 v201, s[20:21]
	s_add_i32 m0, s29, 0x2000
	s_add_i32 s29, s30, s42
	global_load_lds_dwordx4 v215, s[20:21]
	s_add_u32 s20, s20, 0x20080
	s_addc_u32 s21, s21, 0
	s_mov_b32 m0, s29
	s_nop 0
	global_load_lds_dwordx4 v0, s[20:21]
	s_add_i32 m0, s29, 0x2000
	s_nop 0
	global_load_lds_dwordx4 v208, s[20:21]
	s_mov_b32 m0, s47
	s_nop 0
	global_load_lds_dwordx4 v217, s[72:73]
	s_mov_b32 m0, s48
	s_nop 0
	global_load_lds_dwordx4 v219, s[72:73]
	s_waitcnt vmcnt(8)
	s_waitcnt lgkmcnt(0)
	s_barrier
	s_setprio 1
	v_mfma_f32_16x16x32_bf16 v[62:65], v[132:135], v[164:167], v[62:65]
	v_mfma_f32_16x16x32_bf16 v[58:61], v[140:143], v[164:167], v[58:61]
	v_mfma_f32_16x16x32_bf16 v[46:49], v[132:135], v[172:175], v[46:49]
	v_mfma_f32_16x16x32_bf16 v[42:45], v[140:143], v[172:175], v[42:45]
	v_mfma_f32_16x16x32_bf16 v[30:33], v[132:135], v[180:183], v[30:33]
	v_mfma_f32_16x16x32_bf16 v[26:29], v[140:143], v[180:183], v[26:29]
	v_mfma_f32_16x16x32_bf16 v[14:17], v[132:135], v[188:191], v[14:17]
	v_mfma_f32_16x16x32_bf16 v[10:13], v[140:143], v[188:191], v[10:13]
	v_mfma_f32_16x16x32_bf16 v[62:65], v[136:139], v[168:171], v[62:65]
	v_mfma_f32_16x16x32_bf16 v[58:61], v[144:147], v[168:171], v[58:61]
	v_mfma_f32_16x16x32_bf16 v[46:49], v[136:139], v[176:179], v[46:49]
	v_mfma_f32_16x16x32_bf16 v[42:45], v[144:147], v[176:179], v[42:45]
	v_mfma_f32_16x16x32_bf16 v[30:33], v[136:139], v[184:187], v[30:33]
	v_mfma_f32_16x16x32_bf16 v[26:29], v[144:147], v[184:187], v[26:29]
	v_mfma_f32_16x16x32_bf16 v[14:17], v[136:139], v[192:195], v[14:17]
	v_mfma_f32_16x16x32_bf16 v[10:13], v[144:147], v[192:195], v[10:13]
	s_setprio 0
	s_setprio 1
	s_add_i32 s51, s51, 2
	s_add_u32 s24, s24, 0x100
	s_addc_u32 s31, s31, 0
	s_add_u32 s16, s16, 0x100
	s_addc_u32 s17, s17, 0
	s_cmp_gt_u32 s51, 5
	s_cbranch_scc1 .Lrot_skip_444
	s_add_u32 s20, s16, 0xfffe0080
	s_addc_u32 s21, s17, -1
	s_cmp_eq_u32 s51, 4
	s_cselect_b32 s73, s1, s21
	s_cselect_b32 s72, s5, s20
	s_cselect_b32 s21, s15, s31
	s_cselect_b32 s20, s23, s24
.Lrot_skip_444:
	s_cmp_gt_u32 s51, 5
	v_mfma_f32_16x16x32_bf16 v[54:57], v[148:151], v[164:167], v[54:57]
	v_mfma_f32_16x16x32_bf16 v[50:53], v[156:159], v[164:167], v[50:53]
	v_mfma_f32_16x16x32_bf16 v[38:41], v[148:151], v[172:175], v[38:41]
	v_mfma_f32_16x16x32_bf16 v[34:37], v[156:159], v[172:175], v[34:37]
	v_mfma_f32_16x16x32_bf16 v[22:25], v[148:151], v[180:183], v[22:25]
	v_mfma_f32_16x16x32_bf16 v[18:21], v[156:159], v[180:183], v[18:21]
	v_mfma_f32_16x16x32_bf16 v[6:9], v[148:151], v[188:191], v[6:9]
	v_mfma_f32_16x16x32_bf16 v[2:5], v[156:159], v[188:191], v[2:5]
	v_mfma_f32_16x16x32_bf16 v[54:57], v[152:155], v[168:171], v[54:57]
	v_mfma_f32_16x16x32_bf16 v[50:53], v[160:163], v[168:171], v[50:53]
	v_mfma_f32_16x16x32_bf16 v[38:41], v[152:155], v[176:179], v[38:41]
	v_mfma_f32_16x16x32_bf16 v[34:37], v[160:163], v[176:179], v[34:37]
	v_mfma_f32_16x16x32_bf16 v[22:25], v[152:155], v[184:187], v[22:25]
	v_mfma_f32_16x16x32_bf16 v[18:21], v[160:163], v[184:187], v[18:21]
	v_mfma_f32_16x16x32_bf16 v[6:9], v[152:155], v[192:195], v[6:9]
	v_mfma_f32_16x16x32_bf16 v[2:5], v[160:163], v[192:195], v[2:5]
	s_barrier
	s_setprio 0
	s_cbranch_scc0 .Lrot_444
	s_and_b64 vcc, exec, s[10:11]
	s_cbranch_vccz .LBB0_447
	s_barrier

; #define PG8_STAGE(bufoff, gbase, voff) do { _Pragma("unroll") for (int _i = 0; _i < 2; ++_i) \
;         __builtin_amdgcn_global_load_lds((const gunsigned*)((const gchar*)(gbase) + (voff)[_i]), (LAS unsigned*)(lds + (bufoff) + ldsw + _i * 8192), 16, 0, 0); } while (0)
; #define PG8_LDA(dst, b, h) do { _Pragma("unroll") for (int m = 0; m < 4; ++m) _Pragma("unroll") for (int k = 0; k < 2; ++k) dst[m][k] = *(const LAS bf16x8*)(lds + PG8_SA(b, h) + aoff + m * 2048 + k * 1024); } while (0)
; #define PG8_LDB(dst, b, h) do { _Pragma("unroll") for (int n = 0; n < 2; ++n) _Pragma("unroll") for (int k = 0; k < 2; ++k) dst[n][k] = *(const LAS bf16x8*)(lds + PG8_SB(b, h) + boff + n * 2048 + k * 1024); } while (0)
; #define PG8_MMA(ai, bj, At, Bt) do { __builtin_amdgcn_s_setprio(1); _Pragma("unroll") for (int m = 0; m < 4; ++m) _Pragma("unroll") for (int n = 0; n < 2; ++n) _Pragma("unroll") for (int k = 0; k < 2; ++k) \
;         acc[ai][bj][m][n] = __builtin_amdgcn_mfma_f32_16x16x32_bf16(Bt[n][k], At[m][k], acc[ai][bj][m][n], 0, 0, 0); __builtin_amdgcn_s_setprio(0); } while (0)
; #define PG8_WAIT_V(n) asm volatile("s_waitcnt vmcnt(" #n ")" ::: "memory")
; #define PG8_WAIT_L(n) asm volatile("s_waitcnt lgkmcnt(" #n ")" ::: "memory")
; #define PG8_BAR __builtin_amdgcn_s_barrier()
; #define PG8_SCHED __builtin_amdgcn_sched_barrier(0)
; template <class Epi, class Sched>
; __device__ __forceinline__ void gemm_phase(LAS unsigned char* lds, const int tid, const Gemm g, const Sched& S, const Epi& E) {
;     ...
;         for (int t = 0; t < nt; t += 2) {
;             const bool last = (t == nt - 2);
;             const gchar* a1 = cA + (size_t)(t + 1) * kstep;
;             const gchar* a2 = last ? nA : cA + (size_t)(t + 2) * kstep; const gchar* b2 = last ? nB : cB + (size_t)(t + 2) * kstep;
;             const gchar* a3 = a2 + kstep; const gchar* b3 = b2 + kstep;
;             PG8_LDB(B0, 0, 0); PG8_LDB(B1, 0, 1); PG8_SCHED; PG8_LDA(At, 0, 0); PG8_STAGE(PG8_SA(1, 1), a1 + hstep, voffA);
;             PG8_WAIT_V(8); PG8_WAIT_L(0); PG8_BAR; PG8_MMA(0, 0, At, B0); PG8_MMA(0, 1, At, B1); PG8_BAR; PG8_SCHED;
;             PG8_LDA(At, 0, 1); PG8_STAGE(PG8_SB(0, 0), b2, voffB); PG8_STAGE(PG8_SB(0, 1), b2 + hstep, voffB); PG8_STAGE(PG8_SA(0, 0), a2, voffA);
;             PG8_WAIT_V(8); PG8_WAIT_L(0); PG8_BAR; PG8_MMA(1, 0, At, B0); PG8_MMA(1, 1, At, B1); PG8_BAR; PG8_SCHED;
.LBB0_559:
	s_add_u32 s20, s60, 0xfffc0080
	s_addc_u32 s21, s61, -1
	s_cmp_eq_u32 s46, 12
	s_cselect_b32 s63, s9, s21
	s_cselect_b32 s62, s42, s20
	s_cselect_b32 s21, s7, s45
	s_cselect_b32 s20, s43, s44
.Lrot_559:
	s_add_i32 s29, 0, 0x10000
	s_add_i32 s30, 0, 0x14000
	v_add_u32_e32 v152, s29, v165
	v_add_u32_e32 v160, s30, v165
	ds_read_b128 v[130:133], v152
	ds_read_b128 v[144:147], v152 offset:1024
	ds_read_b128 v[148:151], v152 offset:2048
	ds_read_b128 v[152:155], v152 offset:3072
	ds_read_b128 v[156:159], v160
	ds_read_b128 v[170:173], v160 offset:1024
	ds_read_b128 v[174:177], v160 offset:2048
	ds_read_b128 v[178:181], v160 offset:3072
	s_add_i32 m0, s34, 0xc000
	ds_read_b128 v[182:185], v169
	ds_read_b128 v[186:189], v169 offset:1024
	ds_read_b128 v[190:193], v169 offset:2048
	ds_read_b128 v[204:207], v169 offset:3072
	ds_read_b128 v[210:213], v169 offset:4096
	ds_read_b128 v[214:217], v169 offset:5120
	ds_read_b128 v[218:221], v169 offset:6144
	ds_read_b128 v[222:225], v169 offset:7168
	global_load_lds_dwordx4 v142, s[60:61]
	s_add_i32 m0, s34, 0xe000
	s_nop 0
	global_load_lds_dwordx4 v140, s[60:61]
	s_waitcnt vmcnt(8)
	s_waitcnt lgkmcnt(0)
	s_barrier
	s_setprio 1
	v_mfma_f32_16x16x32_bf16 v[126:129], v[130:133], v[182:185], v[126:129]
	v_mfma_f32_16x16x32_bf16 v[122:125], v[148:151], v[182:185], v[122:125]
	v_mfma_f32_16x16x32_bf16 v[118:121], v[130:133], v[190:193], v[118:121]
	v_mfma_f32_16x16x32_bf16 v[110:113], v[148:151], v[190:193], v[110:113]
	v_mfma_f32_16x16x32_bf16 v[102:105], v[130:133], v[210:213], v[102:105]
	v_mfma_f32_16x16x32_bf16 v[94:97], v[148:151], v[210:213], v[94:97]
	v_mfma_f32_16x16x32_bf16 v[86:89], v[130:133], v[218:221], v[86:89]
	v_mfma_f32_16x16x32_bf16 v[78:81], v[148:151], v[218:221], v[78:81]
	v_mfma_f32_16x16x32_bf16 v[126:129], v[144:147], v[186:189], v[126:129]
	v_mfma_f32_16x16x32_bf16 v[122:125], v[152:155], v[186:189], v[122:125]
	v_mfma_f32_16x16x32_bf16 v[118:121], v[144:147], v[204:207], v[118:121]
	v_mfma_f32_16x16x32_bf16 v[110:113], v[152:155], v[204:207], v[110:113]
	v_mfma_f32_16x16x32_bf16 v[102:105], v[144:147], v[214:217], v[102:105]
	v_mfma_f32_16x16x32_bf16 v[94:97], v[152:155], v[214:217], v[94:97]
	v_mfma_f32_16x16x32_bf16 v[86:89], v[144:147], v[222:225], v[86:89]
	v_mfma_f32_16x16x32_bf16 v[78:81], v[152:155], v[222:225], v[78:81]
	s_setprio 0
	s_setprio 1
	v_mfma_f32_16x16x32_bf16 v[114:117], v[156:159], v[182:185], v[114:117]
	v_mfma_f32_16x16x32_bf16 v[106:109], v[174:177], v[182:185], v[106:109]
	v_mfma_f32_16x16x32_bf16 v[98:101], v[156:159], v[190:193], v[98:101]
	v_mfma_f32_16x16x32_bf16 v[90:93], v[174:177], v[190:193], v[90:93]
	v_mfma_f32_16x16x32_bf16 v[82:85], v[156:159], v[210:213], v[82:85]
	v_mfma_f32_16x16x32_bf16 v[74:77], v[174:177], v[210:213], v[74:77]
	v_mfma_f32_16x16x32_bf16 v[70:73], v[156:159], v[218:221], v[70:73]
	v_mfma_f32_16x16x32_bf16 v[66:69], v[174:177], v[218:221], v[66:69]
	v_mfma_f32_16x16x32_bf16 v[114:117], v[170:173], v[186:189], v[114:117]
	v_mfma_f32_16x16x32_bf16 v[106:109], v[178:181], v[186:189], v[106:109]
	v_mfma_f32_16x16x32_bf16 v[98:101], v[170:173], v[204:207], v[98:101]
	v_mfma_f32_16x16x32_bf16 v[90:93], v[178:181], v[204:207], v[90:93]
	v_mfma_f32_16x16x32_bf16 v[82:85], v[170:173], v[214:217], v[82:85]
	v_mfma_f32_16x16x32_bf16 v[74:77], v[178:181], v[214:217], v[74:77]
	v_mfma_f32_16x16x32_bf16 v[70:73], v[170:173], v[222:225], v[70:73]
	v_mfma_f32_16x16x32_bf16 v[66:69], v[178:181], v[222:225], v[66:69]
	s_barrier
	s_setprio 0
	s_add_i32 s29, s29, s12
	s_mov_b32 m0, s29
	ds_read_b128 v[182:185], v169 offset:16384
	ds_read_b128 v[186:189], v169 offset:17408
	ds_read_b128 v[190:193], v169 offset:18432
	ds_read_b128 v[204:207], v169 offset:19456
	ds_read_b128 v[210:213], v169 offset:20480
	ds_read_b128 v[214:217], v169 offset:21504
	ds_read_b128 v[218:221], v169 offset:22528
	ds_read_b128 v[222:225], v169 offset:23552
	global_load_lds_dwordx4 v0, s[20:21]
	s_add_i32 m0, s29, 0x2000
	s_add_u32 s48, s20, 0x40000
	s_addc_u32 s49, s21, 0
	s_add_i32 s29, s30, s12
	global_load_lds_dwordx4 v134, s[20:21]
	s_mov_b32 m0, s29
	s_nop 0
	global_load_lds_dwordx4 v0, s[48:49]
	s_add_i32 m0, s29, 0x2000
	s_nop 0
	global_load_lds_dwordx4 v134, s[48:49]
	s_mov_b32 m0, s34
	s_nop 0
	global_load_lds_dwordx4 v138, s[62:63]
	s_mov_b32 m0, s35
	s_nop 0
	global_load_lds_dwordx4 v136, s[62:63]
	s_waitcnt vmcnt(8)
	s_waitcnt lgkmcnt(0)
	s_barrier
	s_setprio 1
	v_mfma_f32_16x16x32_bf16 v[62:65], v[130:133], v[182:185], v[62:65]
	v_mfma_f32_16x16x32_bf16 v[58:61], v[148:151], v[182:185], v[58:61]
	v_mfma_f32_16x16x32_bf16 v[54:57], v[130:133], v[190:193], v[54:57]
	v_mfma_f32_16x16x32_bf16 v[46:49], v[148:151], v[190:193], v[46:49]
	v_mfma_f32_16x16x32_bf16 v[38:41], v[130:133], v[210:213], v[38:41]
	v_mfma_f32_16x16x32_bf16 v[30:33], v[148:151], v[210:213], v[30:33]
	v_mfma_f32_16x16x32_bf16 v[22:25], v[130:133], v[218:221], v[22:25]
	v_mfma_f32_16x16x32_bf16 v[14:17], v[148:151], v[218:221], v[14:17]
	v_mfma_f32_16x16x32_bf16 v[62:65], v[144:147], v[186:189], v[62:65]
	v_mfma_f32_16x16x32_bf16 v[58:61], v[152:155], v[186:189], v[58:61]
	v_mfma_f32_16x16x32_bf16 v[54:57], v[144:147], v[204:207], v[54:57]
	v_mfma_f32_16x16x32_bf16 v[46:49], v[152:155], v[204:207], v[46:49]
	v_mfma_f32_16x16x32_bf16 v[38:41], v[144:147], v[214:217], v[38:41]
	v_mfma_f32_16x16x32_bf16 v[30:33], v[152:155], v[214:217], v[30:33]
	v_mfma_f32_16x16x32_bf16 v[22:25], v[144:147], v[222:225], v[22:25]
	v_mfma_f32_16x16x32_bf16 v[14:17], v[152:155], v[222:225], v[14:17]
	s_setprio 0
	s_setprio 1
	v_mfma_f32_16x16x32_bf16 v[50:53], v[156:159], v[182:185], v[50:53]
	v_mfma_f32_16x16x32_bf16 v[42:45], v[174:177], v[182:185], v[42:45]
	v_mfma_f32_16x16x32_bf16 v[34:37], v[156:159], v[190:193], v[34:37]
	v_mfma_f32_16x16x32_bf16 v[26:29], v[174:177], v[190:193], v[26:29]
	v_mfma_f32_16x16x32_bf16 v[18:21], v[156:159], v[210:213], v[18:21]
	v_mfma_f32_16x16x32_bf16 v[10:13], v[174:177], v[210:213], v[10:13]
	v_mfma_f32_16x16x32_bf16 v[6:9], v[156:159], v[218:221], v[6:9]
	v_mfma_f32_16x16x32_bf16 v[2:5], v[174:177], v[218:221], v[2:5]
	v_mfma_f32_16x16x32_bf16 v[50:53], v[170:173], v[186:189], v[50:53]
	v_mfma_f32_16x16x32_bf16 v[42:45], v[178:181], v[186:189], v[42:45]
	v_mfma_f32_16x16x32_bf16 v[34:37], v[170:173], v[204:207], v[34:37]
	v_mfma_f32_16x16x32_bf16 v[26:29], v[178:181], v[204:207], v[26:29]
	v_mfma_f32_16x16x32_bf16 v[18:21], v[170:173], v[214:217], v[18:21]
	v_mfma_f32_16x16x32_bf16 v[10:13], v[178:181], v[214:217], v[10:13]
	v_mfma_f32_16x16x32_bf16 v[6:9], v[170:173], v[222:225], v[6:9]
	v_mfma_f32_16x16x32_bf16 v[2:5], v[178:181], v[222:225], v[2:5]
	s_barrier
; #define PG8_STAGE(bufoff, gbase, voff) do { _Pragma("unroll") for (int _i = 0; _i < 2; ++_i) \
;         __builtin_amdgcn_global_load_lds((const gunsigned*)((const gchar*)(gbase) + (voff)[_i]), (LAS unsigned*)(lds + (bufoff) + ldsw + _i * 8192), 16, 0, 0); } while (0)
; #define PG8_LDA(dst, b, h) do { _Pragma("unroll") for (int m = 0; m < 4; ++m) _Pragma("unroll") for (int k = 0; k < 2; ++k) dst[m][k] = *(const LAS bf16x8*)(lds + PG8_SA(b, h) + aoff + m * 2048 + k * 1024); } while (0)
; #define PG8_LDB(dst, b, h) do { _Pragma("unroll") for (int n = 0; n < 2; ++n) _Pragma("unroll") for (int k = 0; k < 2; ++k) dst[n][k] = *(const LAS bf16x8*)(lds + PG8_SB(b, h) + boff + n * 2048 + k * 1024); } while (0)
; #define PG8_MMA(ai, bj, At, Bt) do { __builtin_amdgcn_s_setprio(1); _Pragma("unroll") for (int m = 0; m < 4; ++m) _Pragma("unroll") for (int n = 0; n < 2; ++n) _Pragma("unroll") for (int k = 0; k < 2; ++k) \
;         acc[ai][bj][m][n] = __builtin_amdgcn_mfma_f32_16x16x32_bf16(Bt[n][k], At[m][k], acc[ai][bj][m][n], 0, 0, 0); __builtin_amdgcn_s_setprio(0); } while (0)
; #define PG8_WAIT_V(n) asm volatile("s_waitcnt vmcnt(" #n ")" ::: "memory")
; #define PG8_WAIT_L(n) asm volatile("s_waitcnt lgkmcnt(" #n ")" ::: "memory")
; #define PG8_BAR __builtin_amdgcn_s_barrier()
; #define PG8_SCHED __builtin_amdgcn_sched_barrier(0)
; template <class Epi, class Sched>
; __device__ __forceinline__ void gemm_phase(LAS unsigned char* lds, const int tid, const Gemm g, const Sched& S, const Epi& E) {
;     ...
;             const bool last = (t == nt - 2);
;             const gchar* a1 = cA + (size_t)(t + 1) * kstep;
;             const gchar* a2 = last ? nA : cA + (size_t)(t + 2) * kstep; const gchar* b2 = last ? nB : cB + (size_t)(t + 2) * kstep;
;             const gchar* a3 = a2 + kstep; const gchar* b3 = b2 + kstep;
;     ...
;             PG8_LDB(B0, 1, 0); PG8_LDB(B1, 1, 1); PG8_SCHED; PG8_LDA(At, 1, 0); PG8_STAGE(PG8_SA(0, 1), a2 + hstep, voffA);
;             PG8_WAIT_V(8); PG8_WAIT_L(0); PG8_BAR; PG8_MMA(0, 0, At, B0); PG8_MMA(0, 1, At, B1); PG8_BAR; PG8_SCHED;
;             PG8_LDA(At, 1, 1); PG8_STAGE(PG8_SB(1, 0), b3, voffB); PG8_STAGE(PG8_SB(1, 1), b3 + hstep, voffB); PG8_STAGE(PG8_SA(1, 0), a3, voffA);
;             PG8_WAIT_V(8); PG8_WAIT_L(0); PG8_BAR; PG8_MMA(1, 0, At, B0); PG8_MMA(1, 1, At, B1); PG8_BAR; PG8_SCHED;
	s_setprio 0
	s_add_i32 s29, 0, 0x18000
	s_add_i32 s30, 0, 0x1c000
	v_add_u32_e32 v152, s29, v165
	v_add_u32_e32 v162, s30, v165
	ds_read_b128 v[130:133], v152
	ds_read_b128 v[144:147], v152 offset:1024
	ds_read_b128 v[148:151], v152 offset:2048
	ds_read_b128 v[152:155], v152 offset:3072
	ds_read_b128 v[156:159], v162
	ds_read_b128 v[170:173], v162 offset:1024
	ds_read_b128 v[174:177], v162 offset:2048
	ds_read_b128 v[178:181], v162 offset:3072
	s_add_u32 s48, s62, 0x40000
	s_addc_u32 s49, s63, 0
	s_mov_b32 m0, s36
	ds_read_b128 v[182:185], v169 offset:32768
	ds_read_b128 v[186:189], v169 offset:33792
	ds_read_b128 v[190:193], v169 offset:34816
	ds_read_b128 v[204:207], v169 offset:35840
	ds_read_b128 v[210:213], v169 offset:36864
	ds_read_b128 v[214:217], v169 offset:37888
	ds_read_b128 v[218:221], v169 offset:38912
	ds_read_b128 v[222:225], v169 offset:39936
	global_load_lds_dwordx4 v138, s[48:49]
	s_mov_b32 m0, s37
	s_nop 0
	global_load_lds_dwordx4 v136, s[48:49]
	s_waitcnt vmcnt(8)
	s_waitcnt lgkmcnt(0)
	s_barrier
	s_setprio 1
	v_mfma_f32_16x16x32_bf16 v[126:129], v[130:133], v[182:185], v[126:129]
	v_mfma_f32_16x16x32_bf16 v[122:125], v[148:151], v[182:185], v[122:125]
	v_mfma_f32_16x16x32_bf16 v[118:121], v[130:133], v[190:193], v[118:121]
	v_mfma_f32_16x16x32_bf16 v[110:113], v[148:151], v[190:193], v[110:113]
	v_mfma_f32_16x16x32_bf16 v[102:105], v[130:133], v[210:213], v[102:105]
	v_mfma_f32_16x16x32_bf16 v[94:97], v[148:151], v[210:213], v[94:97]
	v_mfma_f32_16x16x32_bf16 v[86:89], v[130:133], v[218:221], v[86:89]
	v_mfma_f32_16x16x32_bf16 v[78:81], v[148:151], v[218:221], v[78:81]
	v_mfma_f32_16x16x32_bf16 v[126:129], v[144:147], v[186:189], v[126:129]
	v_mfma_f32_16x16x32_bf16 v[122:125], v[152:155], v[186:189], v[122:125]
	v_mfma_f32_16x16x32_bf16 v[118:121], v[144:147], v[204:207], v[118:121]
	v_mfma_f32_16x16x32_bf16 v[110:113], v[152:155], v[204:207], v[110:113]
	v_mfma_f32_16x16x32_bf16 v[102:105], v[144:147], v[214:217], v[102:105]
	v_mfma_f32_16x16x32_bf16 v[94:97], v[152:155], v[214:217], v[94:97]
	v_mfma_f32_16x16x32_bf16 v[86:89], v[144:147], v[222:225], v[86:89]
	v_mfma_f32_16x16x32_bf16 v[78:81], v[152:155], v[222:225], v[78:81]
	s_setprio 0
	s_setprio 1
	v_mfma_f32_16x16x32_bf16 v[114:117], v[156:159], v[182:185], v[114:117]
	v_mfma_f32_16x16x32_bf16 v[106:109], v[174:177], v[182:185], v[106:109]
	v_mfma_f32_16x16x32_bf16 v[98:101], v[156:159], v[190:193], v[98:101]
	v_mfma_f32_16x16x32_bf16 v[90:93], v[174:177], v[190:193], v[90:93]
	v_mfma_f32_16x16x32_bf16 v[82:85], v[156:159], v[210:213], v[82:85]
	v_mfma_f32_16x16x32_bf16 v[74:77], v[174:177], v[210:213], v[74:77]
	v_mfma_f32_16x16x32_bf16 v[70:73], v[156:159], v[218:221], v[70:73]
	v_mfma_f32_16x16x32_bf16 v[66:69], v[174:177], v[218:221], v[66:69]
	v_mfma_f32_16x16x32_bf16 v[114:117], v[170:173], v[186:189], v[114:117]
	v_mfma_f32_16x16x32_bf16 v[106:109], v[178:181], v[186:189], v[106:109]
	v_mfma_f32_16x16x32_bf16 v[98:101], v[170:173], v[204:207], v[98:101]
	v_mfma_f32_16x16x32_bf16 v[90:93], v[178:181], v[204:207], v[90:93]
	v_mfma_f32_16x16x32_bf16 v[82:85], v[170:173], v[214:217], v[82:85]
	v_mfma_f32_16x16x32_bf16 v[74:77], v[178:181], v[214:217], v[74:77]
	v_mfma_f32_16x16x32_bf16 v[70:73], v[170:173], v[222:225], v[70:73]
	v_mfma_f32_16x16x32_bf16 v[66:69], v[178:181], v[222:225], v[66:69]
	s_barrier
	s_setprio 0
	s_add_i32 s29, s29, s12
	s_mov_b32 m0, s29
	ds_read_b128 v[182:185], v169 offset:49152
	ds_read_b128 v[186:189], v169 offset:50176
	ds_read_b128 v[190:193], v169 offset:51200
	ds_read_b128 v[204:207], v169 offset:52224
	ds_read_b128 v[210:213], v169 offset:53248
	ds_read_b128 v[214:217], v169 offset:54272
	ds_read_b128 v[218:221], v169 offset:55296
	ds_read_b128 v[222:225], v169 offset:56320
	global_load_lds_dwordx4 v161, s[20:21]
	s_add_i32 m0, s29, 0x2000
	s_add_i32 s29, s30, s12
	global_load_lds_dwordx4 v195, s[20:21]
	s_add_u32 s20, s20, 0x40080
	s_addc_u32 s21, s21, 0
	s_mov_b32 m0, s29
	s_nop 0
	global_load_lds_dwordx4 v0, s[20:21]
	s_add_i32 m0, s29, 0x2000
	s_nop 0
	global_load_lds_dwordx4 v134, s[20:21]
	s_mov_b32 m0, s38
	s_nop 0
	global_load_lds_dwordx4 v201, s[62:63]
	s_mov_b32 m0, s39
	s_nop 0
	global_load_lds_dwordx4 v227, s[62:63]
	s_waitcnt vmcnt(8)
	s_waitcnt lgkmcnt(0)
	s_barrier
	s_setprio 1
	v_mfma_f32_16x16x32_bf16 v[62:65], v[130:133], v[182:185], v[62:65]
	v_mfma_f32_16x16x32_bf16 v[58:61], v[148:151], v[182:185], v[58:61]
	v_mfma_f32_16x16x32_bf16 v[54:57], v[130:133], v[190:193], v[54:57]
	v_mfma_f32_16x16x32_bf16 v[46:49], v[148:151], v[190:193], v[46:49]
	v_mfma_f32_16x16x32_bf16 v[38:41], v[130:133], v[210:213], v[38:41]
	v_mfma_f32_16x16x32_bf16 v[30:33], v[148:151], v[210:213], v[30:33]
	v_mfma_f32_16x16x32_bf16 v[22:25], v[130:133], v[218:221], v[22:25]
	v_mfma_f32_16x16x32_bf16 v[14:17], v[148:151], v[218:221], v[14:17]
	v_mfma_f32_16x16x32_bf16 v[62:65], v[144:147], v[186:189], v[62:65]
	v_mfma_f32_16x16x32_bf16 v[58:61], v[152:155], v[186:189], v[58:61]
	v_mfma_f32_16x16x32_bf16 v[54:57], v[144:147], v[204:207], v[54:57]
	v_mfma_f32_16x16x32_bf16 v[46:49], v[152:155], v[204:207], v[46:49]
	v_mfma_f32_16x16x32_bf16 v[38:41], v[144:147], v[214:217], v[38:41]
	v_mfma_f32_16x16x32_bf16 v[30:33], v[152:155], v[214:217], v[30:33]
	v_mfma_f32_16x16x32_bf16 v[22:25], v[144:147], v[222:225], v[22:25]
	v_mfma_f32_16x16x32_bf16 v[14:17], v[152:155], v[222:225], v[14:17]
	s_setprio 0
	s_setprio 1
	s_add_i32 s46, s46, 2
	s_add_u32 s44, s44, 0x100
	s_addc_u32 s45, s45, 0
	s_add_u32 s60, s60, 0x100
	s_addc_u32 s61, s61, 0
	s_cmp_gt_u32 s46, 13
	s_cbranch_scc1 .Lrot_skip_559
	s_add_u32 s20, s60, 0xfffc0080
	s_addc_u32 s21, s61, -1
	s_cmp_eq_u32 s46, 12
	s_cselect_b32 s63, s9, s21
	s_cselect_b32 s62, s42, s20
	s_cselect_b32 s21, s7, s45
	s_cselect_b32 s20, s43, s44
.Lrot_skip_559:
	s_cmp_gt_u32 s46, 13
	v_mfma_f32_16x16x32_bf16 v[50:53], v[156:159], v[182:185], v[50:53]
	v_mfma_f32_16x16x32_bf16 v[42:45], v[174:177], v[182:185], v[42:45]
	v_mfma_f32_16x16x32_bf16 v[34:37], v[156:159], v[190:193], v[34:37]
	v_mfma_f32_16x16x32_bf16 v[26:29], v[174:177], v[190:193], v[26:29]
	v_mfma_f32_16x16x32_bf16 v[18:21], v[156:159], v[210:213], v[18:21]
	v_mfma_f32_16x16x32_bf16 v[10:13], v[174:177], v[210:213], v[10:13]
	v_mfma_f32_16x16x32_bf16 v[6:9], v[156:159], v[218:221], v[6:9]
	v_mfma_f32_16x16x32_bf16 v[2:5], v[174:177], v[218:221], v[2:5]
	v_mfma_f32_16x16x32_bf16 v[50:53], v[170:173], v[186:189], v[50:53]
	v_mfma_f32_16x16x32_bf16 v[42:45], v[178:181], v[186:189], v[42:45]
	v_mfma_f32_16x16x32_bf16 v[34:37], v[170:173], v[204:207], v[34:37]
	v_mfma_f32_16x16x32_bf16 v[26:29], v[178:181], v[204:207], v[26:29]
	v_mfma_f32_16x16x32_bf16 v[18:21], v[170:173], v[214:217], v[18:21]
	v_mfma_f32_16x16x32_bf16 v[10:13], v[178:181], v[214:217], v[10:13]
	v_mfma_f32_16x16x32_bf16 v[6:9], v[170:173], v[222:225], v[6:9]
	v_mfma_f32_16x16x32_bf16 v[2:5], v[178:181], v[222:225], v[2:5]
	s_barrier
	s_setprio 0
	s_cbranch_scc0 .Lrot_559
	s_and_b64 vcc, exec, s[4:5]
	s_cbranch_vccz .LBB0_562
	s_barrier

; #define PG8_STAGE(bufoff, gbase, voff) do { _Pragma("unroll") for (int _i = 0; _i < 2; ++_i) \
;         __builtin_amdgcn_global_load_lds((const gunsigned*)((const gchar*)(gbase) + (voff)[_i]), (LAS unsigned*)(lds + (bufoff) + ldsw + _i * 8192), 16, 0, 0); } while (0)
; #define PG8_LDA(dst, b, h) do { _Pragma("unroll") for (int m = 0; m < 4; ++m) _Pragma("unroll") for (int k = 0; k < 2; ++k) dst[m][k] = *(const LAS bf16x8*)(lds + PG8_SA(b, h) + aoff + m * 2048 + k * 1024); } while (0)
; #define PG8_LDB(dst, b, h) do { _Pragma("unroll") for (int n = 0; n < 2; ++n) _Pragma("unroll") for (int k = 0; k < 2; ++k) dst[n][k] = *(const LAS bf16x8*)(lds + PG8_SB(b, h) + boff + n * 2048 + k * 1024); } while (0)
; #define PG8_MMA(ai, bj, At, Bt) do { __builtin_amdgcn_s_setprio(1); _Pragma("unroll") for (int m = 0; m < 4; ++m) _Pragma("unroll") for (int n = 0; n < 2; ++n) _Pragma("unroll") for (int k = 0; k < 2; ++k) \
;         acc[ai][bj][m][n] = __builtin_amdgcn_mfma_f32_16x16x32_bf16(Bt[n][k], At[m][k], acc[ai][bj][m][n], 0, 0, 0); __builtin_amdgcn_s_setprio(0); } while (0)
; #define PG8_WAIT_V(n) asm volatile("s_waitcnt vmcnt(" #n ")" ::: "memory")
; #define PG8_WAIT_L(n) asm volatile("s_waitcnt lgkmcnt(" #n ")" ::: "memory")
; #define PG8_BAR __builtin_amdgcn_s_barrier()
; #define PG8_SCHED __builtin_amdgcn_sched_barrier(0)
; template <class Epi, class Sched>
; __device__ __forceinline__ void gemm_phase(LAS unsigned char* lds, const int tid, const Gemm g, const Sched& S, const Epi& E) {
;     ...
;         for (int t = 0; t < nt; t += 2) {
;             const bool last = (t == nt - 2);
;             const gchar* a1 = cA + (size_t)(t + 1) * kstep;
;             const gchar* a2 = last ? nA : cA + (size_t)(t + 2) * kstep; const gchar* b2 = last ? nB : cB + (size_t)(t + 2) * kstep;
;             const gchar* a3 = a2 + kstep; const gchar* b3 = b2 + kstep;
;             PG8_LDB(B0, 0, 0); PG8_LDB(B1, 0, 1); PG8_SCHED; PG8_LDA(At, 0, 0); PG8_STAGE(PG8_SA(1, 1), a1 + hstep, voffA);
;             PG8_WAIT_V(8); PG8_WAIT_L(0); PG8_BAR; PG8_MMA(0, 0, At, B0); PG8_MMA(0, 1, At, B1); PG8_BAR; PG8_SCHED;
;             PG8_LDA(At, 0, 1); PG8_STAGE(PG8_SB(0, 0), b2, voffB); PG8_STAGE(PG8_SB(0, 1), b2 + hstep, voffB); PG8_STAGE(PG8_SA(0, 0), a2, voffA);
;             PG8_WAIT_V(8); PG8_WAIT_L(0); PG8_BAR; PG8_MMA(1, 0, At, B0); PG8_MMA(1, 1, At, B1); PG8_BAR; PG8_SCHED;
.LBB0_598:
	s_add_u32 s20, s62, 0x100
	s_addc_u32 s21, s63, 0
	s_cmp_eq_u32 s45, 40
	s_cselect_b32 s73, s9, s21
	s_cselect_b32 s72, s8, s20
	s_cselect_b32 s67, s61, s44
	s_cselect_b32 s66, s60, s31
.Lrot_598:
	s_add_i32 s29, 0, 0x10000
	s_add_i32 s48, 0, 0x14000
	v_add_u32_e32 v142, s29, v210
	v_add_u32_e32 v158, s48, v210
	ds_read_b128 v[130:133], v142
	ds_read_b128 v[134:137], v142 offset:1024
	ds_read_b128 v[138:141], v142 offset:2048
	ds_read_b128 v[142:145], v142 offset:3072
	ds_read_b128 v[146:149], v158
	ds_read_b128 v[150:153], v158 offset:1024
	ds_read_b128 v[154:157], v158 offset:2048
	ds_read_b128 v[158:161], v158 offset:3072
	s_add_i32 m0, s34, 0xc000
	ds_read_b128 v[162:165], v214
	ds_read_b128 v[166:169], v214 offset:1024
	ds_read_b128 v[170:173], v214 offset:2048
	ds_read_b128 v[174:177], v214 offset:3072
	ds_read_b128 v[188:191], v214 offset:4096
	ds_read_b128 v[192:195], v214 offset:5120
	ds_read_b128 v[204:207], v214 offset:6144
	ds_read_b128 v[216:219], v214 offset:7168
	global_load_lds_dwordx4 v186, s[62:63]
	s_add_i32 m0, s34, 0xe000
	s_nop 0
	global_load_lds_dwordx4 v184, s[62:63]
	s_waitcnt vmcnt(8)
	s_waitcnt lgkmcnt(0)
	s_barrier
	s_setprio 1
	v_mfma_f32_16x16x32_bf16 v[126:129], v[130:133], v[162:165], v[126:129]
	v_mfma_f32_16x16x32_bf16 v[122:125], v[138:141], v[162:165], v[122:125]
	v_mfma_f32_16x16x32_bf16 v[110:113], v[130:133], v[170:173], v[110:113]
	v_mfma_f32_16x16x32_bf16 v[106:109], v[138:141], v[170:173], v[106:109]
	v_mfma_f32_16x16x32_bf16 v[94:97], v[130:133], v[188:191], v[94:97]
	v_mfma_f32_16x16x32_bf16 v[90:93], v[138:141], v[188:191], v[90:93]
	v_mfma_f32_16x16x32_bf16 v[78:81], v[130:133], v[204:207], v[78:81]
	v_mfma_f32_16x16x32_bf16 v[74:77], v[138:141], v[204:207], v[74:77]
	v_mfma_f32_16x16x32_bf16 v[126:129], v[134:137], v[166:169], v[126:129]
	v_mfma_f32_16x16x32_bf16 v[122:125], v[142:145], v[166:169], v[122:125]
	v_mfma_f32_16x16x32_bf16 v[110:113], v[134:137], v[174:177], v[110:113]
	v_mfma_f32_16x16x32_bf16 v[106:109], v[142:145], v[174:177], v[106:109]
	v_mfma_f32_16x16x32_bf16 v[94:97], v[134:137], v[192:195], v[94:97]
	v_mfma_f32_16x16x32_bf16 v[90:93], v[142:145], v[192:195], v[90:93]
	v_mfma_f32_16x16x32_bf16 v[78:81], v[134:137], v[216:219], v[78:81]
	v_mfma_f32_16x16x32_bf16 v[74:77], v[142:145], v[216:219], v[74:77]
	s_setprio 0
	s_setprio 1
	v_mfma_f32_16x16x32_bf16 v[118:121], v[146:149], v[162:165], v[118:121]
	v_mfma_f32_16x16x32_bf16 v[114:117], v[154:157], v[162:165], v[114:117]
	v_mfma_f32_16x16x32_bf16 v[102:105], v[146:149], v[170:173], v[102:105]
	v_mfma_f32_16x16x32_bf16 v[98:101], v[154:157], v[170:173], v[98:101]
	v_mfma_f32_16x16x32_bf16 v[86:89], v[146:149], v[188:191], v[86:89]
	v_mfma_f32_16x16x32_bf16 v[82:85], v[154:157], v[188:191], v[82:85]
	v_mfma_f32_16x16x32_bf16 v[70:73], v[146:149], v[204:207], v[70:73]
	v_mfma_f32_16x16x32_bf16 v[66:69], v[154:157], v[204:207], v[66:69]
	v_mfma_f32_16x16x32_bf16 v[118:121], v[150:153], v[166:169], v[118:121]
	v_mfma_f32_16x16x32_bf16 v[114:117], v[158:161], v[166:169], v[114:117]
	v_mfma_f32_16x16x32_bf16 v[102:105], v[150:153], v[174:177], v[102:105]
	v_mfma_f32_16x16x32_bf16 v[98:101], v[158:161], v[174:177], v[98:101]
	v_mfma_f32_16x16x32_bf16 v[86:89], v[150:153], v[192:195], v[86:89]
	v_mfma_f32_16x16x32_bf16 v[82:85], v[158:161], v[192:195], v[82:85]
	v_mfma_f32_16x16x32_bf16 v[70:73], v[150:153], v[216:219], v[70:73]
	v_mfma_f32_16x16x32_bf16 v[66:69], v[158:161], v[216:219], v[66:69]
	s_barrier
	s_setprio 0
	s_add_i32 s29, s29, s15
	s_mov_b32 m0, s29
	ds_read_b128 v[162:165], v214 offset:16384
	ds_read_b128 v[166:169], v214 offset:17408
	ds_read_b128 v[170:173], v214 offset:18432
	ds_read_b128 v[174:177], v214 offset:19456
	ds_read_b128 v[188:191], v214 offset:20480
	ds_read_b128 v[192:195], v214 offset:21504
	ds_read_b128 v[204:207], v214 offset:22528
	ds_read_b128 v[216:219], v214 offset:23552
	global_load_lds_dwordx4 v0, s[66:67]
	s_add_i32 m0, s29, 0x2000
	s_add_u32 s46, s66, 0xb0000
	s_addc_u32 s47, s67, 0
	s_add_i32 s29, s48, s15
	global_load_lds_dwordx4 v182, s[66:67]
	s_mov_b32 m0, s29
	s_nop 0
	global_load_lds_dwordx4 v0, s[46:47]
	s_add_i32 m0, s29, 0x2000
	s_nop 0
	global_load_lds_dwordx4 v182, s[46:47]
	s_mov_b32 m0, s34
	s_nop 0
	global_load_lds_dwordx4 v178, s[72:73]
	s_mov_b32 m0, s12
	s_nop 0
	global_load_lds_dwordx4 v180, s[72:73]
	s_waitcnt vmcnt(8)
	s_waitcnt lgkmcnt(0)
	s_barrier
	s_setprio 1
	v_mfma_f32_16x16x32_bf16 v[62:65], v[130:133], v[162:165], v[62:65]
	v_mfma_f32_16x16x32_bf16 v[58:61], v[138:141], v[162:165], v[58:61]
	v_mfma_f32_16x16x32_bf16 v[46:49], v[130:133], v[170:173], v[46:49]
	v_mfma_f32_16x16x32_bf16 v[42:45], v[138:141], v[170:173], v[42:45]
	v_mfma_f32_16x16x32_bf16 v[30:33], v[130:133], v[188:191], v[30:33]
	v_mfma_f32_16x16x32_bf16 v[26:29], v[138:141], v[188:191], v[26:29]
	v_mfma_f32_16x16x32_bf16 v[14:17], v[130:133], v[204:207], v[14:17]
	v_mfma_f32_16x16x32_bf16 v[10:13], v[138:141], v[204:207], v[10:13]
	v_mfma_f32_16x16x32_bf16 v[62:65], v[134:137], v[166:169], v[62:65]
	v_mfma_f32_16x16x32_bf16 v[58:61], v[142:145], v[166:169], v[58:61]
	v_mfma_f32_16x16x32_bf16 v[46:49], v[134:137], v[174:177], v[46:49]
	v_mfma_f32_16x16x32_bf16 v[42:45], v[142:145], v[174:177], v[42:45]
	v_mfma_f32_16x16x32_bf16 v[30:33], v[134:137], v[192:195], v[30:33]
	v_mfma_f32_16x16x32_bf16 v[26:29], v[142:145], v[192:195], v[26:29]
	v_mfma_f32_16x16x32_bf16 v[14:17], v[134:137], v[216:219], v[14:17]
	v_mfma_f32_16x16x32_bf16 v[10:13], v[142:145], v[216:219], v[10:13]
	s_setprio 0
	s_setprio 1
	v_mfma_f32_16x16x32_bf16 v[54:57], v[146:149], v[162:165], v[54:57]
	v_mfma_f32_16x16x32_bf16 v[50:53], v[154:157], v[162:165], v[50:53]
	v_mfma_f32_16x16x32_bf16 v[38:41], v[146:149], v[170:173], v[38:41]
	v_mfma_f32_16x16x32_bf16 v[34:37], v[154:157], v[170:173], v[34:37]
	v_mfma_f32_16x16x32_bf16 v[22:25], v[146:149], v[188:191], v[22:25]
	v_mfma_f32_16x16x32_bf16 v[18:21], v[154:157], v[188:191], v[18:21]
	v_mfma_f32_16x16x32_bf16 v[6:9], v[146:149], v[204:207], v[6:9]
	v_mfma_f32_16x16x32_bf16 v[2:5], v[154:157], v[204:207], v[2:5]
	v_mfma_f32_16x16x32_bf16 v[54:57], v[150:153], v[166:169], v[54:57]
	v_mfma_f32_16x16x32_bf16 v[50:53], v[158:161], v[166:169], v[50:53]
	v_mfma_f32_16x16x32_bf16 v[38:41], v[150:153], v[174:177], v[38:41]
	v_mfma_f32_16x16x32_bf16 v[34:37], v[158:161], v[174:177], v[34:37]
	v_mfma_f32_16x16x32_bf16 v[22:25], v[150:153], v[192:195], v[22:25]
	v_mfma_f32_16x16x32_bf16 v[18:21], v[158:161], v[192:195], v[18:21]
	v_mfma_f32_16x16x32_bf16 v[6:9], v[150:153], v[216:219], v[6:9]
	v_mfma_f32_16x16x32_bf16 v[2:5], v[158:161], v[216:219], v[2:5]
	s_barrier
; #define PG8_STAGE(bufoff, gbase, voff) do { _Pragma("unroll") for (int _i = 0; _i < 2; ++_i) \
;         __builtin_amdgcn_global_load_lds((const gunsigned*)((const gchar*)(gbase) + (voff)[_i]), (LAS unsigned*)(lds + (bufoff) + ldsw + _i * 8192), 16, 0, 0); } while (0)
; #define PG8_LDA(dst, b, h) do { _Pragma("unroll") for (int m = 0; m < 4; ++m) _Pragma("unroll") for (int k = 0; k < 2; ++k) dst[m][k] = *(const LAS bf16x8*)(lds + PG8_SA(b, h) + aoff + m * 2048 + k * 1024); } while (0)
; #define PG8_LDB(dst, b, h) do { _Pragma("unroll") for (int n = 0; n < 2; ++n) _Pragma("unroll") for (int k = 0; k < 2; ++k) dst[n][k] = *(const LAS bf16x8*)(lds + PG8_SB(b, h) + boff + n * 2048 + k * 1024); } while (0)
; #define PG8_MMA(ai, bj, At, Bt) do { __builtin_amdgcn_s_setprio(1); _Pragma("unroll") for (int m = 0; m < 4; ++m) _Pragma("unroll") for (int n = 0; n < 2; ++n) _Pragma("unroll") for (int k = 0; k < 2; ++k) \
;         acc[ai][bj][m][n] = __builtin_amdgcn_mfma_f32_16x16x32_bf16(Bt[n][k], At[m][k], acc[ai][bj][m][n], 0, 0, 0); __builtin_amdgcn_s_setprio(0); } while (0)
; #define PG8_WAIT_V(n) asm volatile("s_waitcnt vmcnt(" #n ")" ::: "memory")
; #define PG8_WAIT_L(n) asm volatile("s_waitcnt lgkmcnt(" #n ")" ::: "memory")
; #define PG8_BAR __builtin_amdgcn_s_barrier()
; #define PG8_SCHED __builtin_amdgcn_sched_barrier(0)
; template <class Epi, class Sched>
; __device__ __forceinline__ void gemm_phase(LAS unsigned char* lds, const int tid, const Gemm g, const Sched& S, const Epi& E) {
;     ...
;             const bool last = (t == nt - 2);
;             const gchar* a1 = cA + (size_t)(t + 1) * kstep;
;             const gchar* a2 = last ? nA : cA + (size_t)(t + 2) * kstep; const gchar* b2 = last ? nB : cB + (size_t)(t + 2) * kstep;
;             const gchar* a3 = a2 + kstep; const gchar* b3 = b2 + kstep;
;     ...
;             PG8_LDB(B0, 1, 0); PG8_LDB(B1, 1, 1); PG8_SCHED; PG8_LDA(At, 1, 0); PG8_STAGE(PG8_SA(0, 1), a2 + hstep, voffA);
;             PG8_WAIT_V(8); PG8_WAIT_L(0); PG8_BAR; PG8_MMA(0, 0, At, B0); PG8_MMA(0, 1, At, B1); PG8_BAR; PG8_SCHED;
;             PG8_LDA(At, 1, 1); PG8_STAGE(PG8_SB(1, 0), b3, voffB); PG8_STAGE(PG8_SB(1, 1), b3 + hstep, voffB); PG8_STAGE(PG8_SA(1, 0), a3, voffA);
;             PG8_WAIT_V(8); PG8_WAIT_L(0); PG8_BAR; PG8_MMA(1, 0, At, B0); PG8_MMA(1, 1, At, B1); PG8_BAR; PG8_SCHED;
	s_setprio 0
	s_add_i32 s29, 0, 0x18000
	s_add_i32 s48, 0, 0x1c000
	v_add_u32_e32 v142, s29, v210
	v_add_u32_e32 v158, s48, v210
	ds_read_b128 v[130:133], v142
	ds_read_b128 v[134:137], v142 offset:1024
	ds_read_b128 v[138:141], v142 offset:2048
	ds_read_b128 v[142:145], v142 offset:3072
	ds_read_b128 v[146:149], v158
	ds_read_b128 v[150:153], v158 offset:1024
	ds_read_b128 v[154:157], v158 offset:2048
	ds_read_b128 v[158:161], v158 offset:3072
	s_add_u32 s46, s72, 0xb0000
	s_addc_u32 s47, s73, 0
	s_mov_b32 m0, s35
	ds_read_b128 v[162:165], v214 offset:32768
	ds_read_b128 v[166:169], v214 offset:33792
	ds_read_b128 v[170:173], v214 offset:34816
	ds_read_b128 v[174:177], v214 offset:35840
	ds_read_b128 v[188:191], v214 offset:36864
	ds_read_b128 v[192:195], v214 offset:37888
	ds_read_b128 v[204:207], v214 offset:38912
	ds_read_b128 v[216:219], v214 offset:39936
	global_load_lds_dwordx4 v178, s[46:47]
	s_mov_b32 m0, s36
	s_nop 0
	global_load_lds_dwordx4 v180, s[46:47]
	s_waitcnt vmcnt(8)
	s_waitcnt lgkmcnt(0)
	s_barrier
	s_setprio 1
	v_mfma_f32_16x16x32_bf16 v[126:129], v[130:133], v[162:165], v[126:129]
	v_mfma_f32_16x16x32_bf16 v[122:125], v[138:141], v[162:165], v[122:125]
	v_mfma_f32_16x16x32_bf16 v[110:113], v[130:133], v[170:173], v[110:113]
	v_mfma_f32_16x16x32_bf16 v[106:109], v[138:141], v[170:173], v[106:109]
	v_mfma_f32_16x16x32_bf16 v[94:97], v[130:133], v[188:191], v[94:97]
	v_mfma_f32_16x16x32_bf16 v[90:93], v[138:141], v[188:191], v[90:93]
	v_mfma_f32_16x16x32_bf16 v[78:81], v[130:133], v[204:207], v[78:81]
	v_mfma_f32_16x16x32_bf16 v[74:77], v[138:141], v[204:207], v[74:77]
	v_mfma_f32_16x16x32_bf16 v[126:129], v[134:137], v[166:169], v[126:129]
	v_mfma_f32_16x16x32_bf16 v[122:125], v[142:145], v[166:169], v[122:125]
	v_mfma_f32_16x16x32_bf16 v[110:113], v[134:137], v[174:177], v[110:113]
	v_mfma_f32_16x16x32_bf16 v[106:109], v[142:145], v[174:177], v[106:109]
	v_mfma_f32_16x16x32_bf16 v[94:97], v[134:137], v[192:195], v[94:97]
	v_mfma_f32_16x16x32_bf16 v[90:93], v[142:145], v[192:195], v[90:93]
	v_mfma_f32_16x16x32_bf16 v[78:81], v[134:137], v[216:219], v[78:81]
	v_mfma_f32_16x16x32_bf16 v[74:77], v[142:145], v[216:219], v[74:77]
	s_setprio 0
	s_setprio 1
	v_mfma_f32_16x16x32_bf16 v[118:121], v[146:149], v[162:165], v[118:121]
	v_mfma_f32_16x16x32_bf16 v[114:117], v[154:157], v[162:165], v[114:117]
	v_mfma_f32_16x16x32_bf16 v[102:105], v[146:149], v[170:173], v[102:105]
	v_mfma_f32_16x16x32_bf16 v[98:101], v[154:157], v[170:173], v[98:101]
	v_mfma_f32_16x16x32_bf16 v[86:89], v[146:149], v[188:191], v[86:89]
	v_mfma_f32_16x16x32_bf16 v[82:85], v[154:157], v[188:191], v[82:85]
	v_mfma_f32_16x16x32_bf16 v[70:73], v[146:149], v[204:207], v[70:73]
	v_mfma_f32_16x16x32_bf16 v[66:69], v[154:157], v[204:207], v[66:69]
	v_mfma_f32_16x16x32_bf16 v[118:121], v[150:153], v[166:169], v[118:121]
	v_mfma_f32_16x16x32_bf16 v[114:117], v[158:161], v[166:169], v[114:117]
	v_mfma_f32_16x16x32_bf16 v[102:105], v[150:153], v[174:177], v[102:105]
	v_mfma_f32_16x16x32_bf16 v[98:101], v[158:161], v[174:177], v[98:101]
	v_mfma_f32_16x16x32_bf16 v[86:89], v[150:153], v[192:195], v[86:89]
	v_mfma_f32_16x16x32_bf16 v[82:85], v[158:161], v[192:195], v[82:85]
	v_mfma_f32_16x16x32_bf16 v[70:73], v[150:153], v[216:219], v[70:73]
	v_mfma_f32_16x16x32_bf16 v[66:69], v[158:161], v[216:219], v[66:69]
	s_barrier
	s_setprio 0
	s_add_i32 s29, s29, s15
	s_mov_b32 m0, s29
	ds_read_b128 v[162:165], v214 offset:49152
	ds_read_b128 v[166:169], v214 offset:50176
	ds_read_b128 v[170:173], v214 offset:51200
	ds_read_b128 v[174:177], v214 offset:52224
	ds_read_b128 v[188:191], v214 offset:53248
	ds_read_b128 v[192:195], v214 offset:54272
	ds_read_b128 v[204:207], v214 offset:55296
	ds_read_b128 v[216:219], v214 offset:56320
	global_load_lds_dwordx4 v221, s[66:67]
	s_add_i32 m0, s29, 0x2000
	s_add_u32 s46, s66, 0xb0080
	s_addc_u32 s47, s67, 0
	s_add_i32 s29, s48, s15
	global_load_lds_dwordx4 v223, s[66:67]
	s_mov_b32 m0, s29
	s_nop 0
	global_load_lds_dwordx4 v0, s[46:47]
	s_add_i32 m0, s29, 0x2000
	s_nop 0
	global_load_lds_dwordx4 v182, s[46:47]
	s_mov_b32 m0, s37
	s_nop 0
	global_load_lds_dwordx4 v225, s[72:73]
	s_mov_b32 m0, s38
	s_nop 0
	global_load_lds_dwordx4 v227, s[72:73]
	s_waitcnt vmcnt(8)
	s_waitcnt lgkmcnt(0)
	s_barrier
	s_setprio 1
	v_mfma_f32_16x16x32_bf16 v[62:65], v[130:133], v[162:165], v[62:65]
	v_mfma_f32_16x16x32_bf16 v[58:61], v[138:141], v[162:165], v[58:61]
	v_mfma_f32_16x16x32_bf16 v[46:49], v[130:133], v[170:173], v[46:49]
	v_mfma_f32_16x16x32_bf16 v[42:45], v[138:141], v[170:173], v[42:45]
	v_mfma_f32_16x16x32_bf16 v[30:33], v[130:133], v[188:191], v[30:33]
	v_mfma_f32_16x16x32_bf16 v[26:29], v[138:141], v[188:191], v[26:29]
	v_mfma_f32_16x16x32_bf16 v[14:17], v[130:133], v[204:207], v[14:17]
	v_mfma_f32_16x16x32_bf16 v[10:13], v[138:141], v[204:207], v[10:13]
	v_mfma_f32_16x16x32_bf16 v[62:65], v[134:137], v[166:169], v[62:65]
	v_mfma_f32_16x16x32_bf16 v[58:61], v[142:145], v[166:169], v[58:61]
	v_mfma_f32_16x16x32_bf16 v[46:49], v[134:137], v[174:177], v[46:49]
	v_mfma_f32_16x16x32_bf16 v[42:45], v[142:145], v[174:177], v[42:45]
	v_mfma_f32_16x16x32_bf16 v[30:33], v[134:137], v[192:195], v[30:33]
	v_mfma_f32_16x16x32_bf16 v[26:29], v[142:145], v[192:195], v[26:29]
	v_mfma_f32_16x16x32_bf16 v[14:17], v[134:137], v[216:219], v[14:17]
	v_mfma_f32_16x16x32_bf16 v[10:13], v[142:145], v[216:219], v[10:13]
	s_setprio 0
	s_setprio 1
	s_add_i32 s45, s45, 2
	s_add_u32 s31, s31, 0x100
	s_addc_u32 s44, s44, 0
	s_cmp_gt_u32 s45, 41
	s_mov_b64 s[62:63], s[20:21]
	s_cbranch_scc1 .Lrot_skip_598
	s_add_u32 s20, s62, 0x100
	s_addc_u32 s21, s63, 0
	s_cmp_eq_u32 s45, 40
	s_cselect_b32 s73, s9, s21
	s_cselect_b32 s72, s8, s20
	s_cselect_b32 s67, s61, s44
	s_cselect_b32 s66, s60, s31
.Lrot_skip_598:
	s_cmp_gt_u32 s45, 41
	v_mfma_f32_16x16x32_bf16 v[54:57], v[146:149], v[162:165], v[54:57]
	v_mfma_f32_16x16x32_bf16 v[50:53], v[154:157], v[162:165], v[50:53]
	v_mfma_f32_16x16x32_bf16 v[38:41], v[146:149], v[170:173], v[38:41]
	v_mfma_f32_16x16x32_bf16 v[34:37], v[154:157], v[170:173], v[34:37]
	v_mfma_f32_16x16x32_bf16 v[22:25], v[146:149], v[188:191], v[22:25]
	v_mfma_f32_16x16x32_bf16 v[18:21], v[154:157], v[188:191], v[18:21]
	v_mfma_f32_16x16x32_bf16 v[6:9], v[146:149], v[204:207], v[6:9]
	v_mfma_f32_16x16x32_bf16 v[2:5], v[154:157], v[204:207], v[2:5]
	v_mfma_f32_16x16x32_bf16 v[54:57], v[150:153], v[166:169], v[54:57]
	v_mfma_f32_16x16x32_bf16 v[50:53], v[158:161], v[166:169], v[50:53]
	v_mfma_f32_16x16x32_bf16 v[38:41], v[150:153], v[174:177], v[38:41]
	v_mfma_f32_16x16x32_bf16 v[34:37], v[158:161], v[174:177], v[34:37]
	v_mfma_f32_16x16x32_bf16 v[22:25], v[150:153], v[192:195], v[22:25]
	v_mfma_f32_16x16x32_bf16 v[18:21], v[158:161], v[192:195], v[18:21]
	v_mfma_f32_16x16x32_bf16 v[6:9], v[150:153], v[216:219], v[6:9]
	v_mfma_f32_16x16x32_bf16 v[2:5], v[158:161], v[216:219], v[2:5]
	s_barrier
	s_setprio 0
	s_cbranch_scc0 .Lrot_598
	s_and_b64 vcc, exec, s[58:59]
	s_cbranch_vccz .LBB0_601
	s_barrier

; #define PG8_STAGE(bufoff, gbase, voff) do { _Pragma("unroll") for (int _i = 0; _i < 2; ++_i) \
;         __builtin_amdgcn_global_load_lds((const gunsigned*)((const gchar*)(gbase) + (voff)[_i]), (LAS unsigned*)(lds + (bufoff) + ldsw + _i * 8192), 16, 0, 0); } while (0)
; #define PG8_LDA(dst, b, h) do { _Pragma("unroll") for (int m = 0; m < 4; ++m) _Pragma("unroll") for (int k = 0; k < 2; ++k) dst[m][k] = *(const LAS bf16x8*)(lds + PG8_SA(b, h) + aoff + m * 2048 + k * 1024); } while (0)
; #define PG8_LDB(dst, b, h) do { _Pragma("unroll") for (int n = 0; n < 2; ++n) _Pragma("unroll") for (int k = 0; k < 2; ++k) dst[n][k] = *(const LAS bf16x8*)(lds + PG8_SB(b, h) + boff + n * 2048 + k * 1024); } while (0)
; #define PG8_MMA(ai, bj, At, Bt) do { __builtin_amdgcn_s_setprio(1); _Pragma("unroll") for (int m = 0; m < 4; ++m) _Pragma("unroll") for (int n = 0; n < 2; ++n) _Pragma("unroll") for (int k = 0; k < 2; ++k) \
;         acc[ai][bj][m][n] = __builtin_amdgcn_mfma_f32_16x16x32_bf16(Bt[n][k], At[m][k], acc[ai][bj][m][n], 0, 0, 0); __builtin_amdgcn_s_setprio(0); } while (0)
; #define PG8_WAIT_V(n) asm volatile("s_waitcnt vmcnt(" #n ")" ::: "memory")
; #define PG8_WAIT_L(n) asm volatile("s_waitcnt lgkmcnt(" #n ")" ::: "memory")
; #define PG8_BAR __builtin_amdgcn_s_barrier()
; #define PG8_SCHED __builtin_amdgcn_sched_barrier(0)
; template <class Epi, class Sched>
; __device__ __forceinline__ void gemm_phase(LAS unsigned char* lds, const int tid, const Gemm g, const Sched& S, const Epi& E) {
;     ...
;         for (int t = 0; t < nt; t += 2) {
;             const bool last = (t == nt - 2);
;             const gchar* a1 = cA + (size_t)(t + 1) * kstep;
;             const gchar* a2 = last ? nA : cA + (size_t)(t + 2) * kstep; const gchar* b2 = last ? nB : cB + (size_t)(t + 2) * kstep;
;             const gchar* a3 = a2 + kstep; const gchar* b3 = b2 + kstep;
;             PG8_LDB(B0, 0, 0); PG8_LDB(B1, 0, 1); PG8_SCHED; PG8_LDA(At, 0, 0); PG8_STAGE(PG8_SA(1, 1), a1 + hstep, voffA);
;             PG8_WAIT_V(8); PG8_WAIT_L(0); PG8_BAR; PG8_MMA(0, 0, At, B0); PG8_MMA(0, 1, At, B1); PG8_BAR; PG8_SCHED;
;             PG8_LDA(At, 0, 1); PG8_STAGE(PG8_SB(0, 0), b2, voffB); PG8_STAGE(PG8_SB(0, 1), b2 + hstep, voffB); PG8_STAGE(PG8_SA(0, 0), a2, voffA);
;             PG8_WAIT_V(8); PG8_WAIT_L(0); PG8_BAR; PG8_MMA(1, 0, At, B0); PG8_MMA(1, 1, At, B1); PG8_BAR; PG8_SCHED;
.LBB0_647:
	s_add_u32 s20, s58, 0xfffc0080
	s_addc_u32 s21, s59, -1
	s_cmp_eq_u32 s41, 12
	s_cselect_b32 s61, s9, s21
	s_cselect_b32 s60, s37, s20
	s_cselect_b32 s21, s7, s40
	s_cselect_b32 s20, s38, s39
.Lrot_647:
	s_add_i32 s42, 0, 0x10000
	v_add_u32_e32 v140, s42, v143
	s_add_i32 s44, 0, 0x14000
	ds_read_b128 v[146:149], v140
	ds_read_b128 v[150:153], v140 offset:1024
	ds_read_b128 v[154:157], v140 offset:2048
	ds_read_b128 v[158:161], v140 offset:3072
	v_add_u32_e32 v140, s44, v143
	ds_read_b128 v[162:165], v140
	ds_read_b128 v[166:169], v140 offset:1024
	ds_read_b128 v[170:173], v140 offset:2048
	ds_read_b128 v[174:177], v140 offset:3072
	s_add_i32 m0, s23, 0xc000
	ds_read_b128 v[178:181], v145
	ds_read_b128 v[182:185], v145 offset:1024
	ds_read_b128 v[186:189], v145 offset:2048
	ds_read_b128 v[190:193], v145 offset:3072
	ds_read_b128 v[204:207], v145 offset:4096
	ds_read_b128 v[208:211], v145 offset:5120
	ds_read_b128 v[212:215], v145 offset:6144
	ds_read_b128 v[216:219], v145 offset:7168
	global_load_lds_dwordx4 v138, s[58:59]
	s_add_i32 m0, s23, 0xe000
	s_nop 0
	global_load_lds_dwordx4 v136, s[58:59]
	s_waitcnt vmcnt(8)
	s_waitcnt lgkmcnt(0)
	s_barrier
	s_setprio 1
	v_mfma_f32_16x16x32_bf16 v[126:129], v[146:149], v[178:181], v[126:129]
	v_mfma_f32_16x16x32_bf16 v[122:125], v[154:157], v[178:181], v[122:125]
	v_mfma_f32_16x16x32_bf16 v[110:113], v[146:149], v[186:189], v[110:113]
	v_mfma_f32_16x16x32_bf16 v[106:109], v[154:157], v[186:189], v[106:109]
	v_mfma_f32_16x16x32_bf16 v[94:97], v[146:149], v[204:207], v[94:97]
	v_mfma_f32_16x16x32_bf16 v[90:93], v[154:157], v[204:207], v[90:93]
	v_mfma_f32_16x16x32_bf16 v[78:81], v[146:149], v[212:215], v[78:81]
	v_mfma_f32_16x16x32_bf16 v[74:77], v[154:157], v[212:215], v[74:77]
	v_mfma_f32_16x16x32_bf16 v[126:129], v[150:153], v[182:185], v[126:129]
	v_mfma_f32_16x16x32_bf16 v[122:125], v[158:161], v[182:185], v[122:125]
	v_mfma_f32_16x16x32_bf16 v[110:113], v[150:153], v[190:193], v[110:113]
	v_mfma_f32_16x16x32_bf16 v[106:109], v[158:161], v[190:193], v[106:109]
	v_mfma_f32_16x16x32_bf16 v[94:97], v[150:153], v[208:211], v[94:97]
	v_mfma_f32_16x16x32_bf16 v[90:93], v[158:161], v[208:211], v[90:93]
	v_mfma_f32_16x16x32_bf16 v[78:81], v[150:153], v[216:219], v[78:81]
	v_mfma_f32_16x16x32_bf16 v[74:77], v[158:161], v[216:219], v[74:77]
	s_setprio 0
	s_setprio 1
	v_mfma_f32_16x16x32_bf16 v[118:121], v[162:165], v[178:181], v[118:121]
	v_mfma_f32_16x16x32_bf16 v[114:117], v[170:173], v[178:181], v[114:117]
	v_mfma_f32_16x16x32_bf16 v[102:105], v[162:165], v[186:189], v[102:105]
	v_mfma_f32_16x16x32_bf16 v[98:101], v[170:173], v[186:189], v[98:101]
	v_mfma_f32_16x16x32_bf16 v[86:89], v[162:165], v[204:207], v[86:89]
	v_mfma_f32_16x16x32_bf16 v[82:85], v[170:173], v[204:207], v[82:85]
	v_mfma_f32_16x16x32_bf16 v[70:73], v[162:165], v[212:215], v[70:73]
	v_mfma_f32_16x16x32_bf16 v[66:69], v[170:173], v[212:215], v[66:69]
	v_mfma_f32_16x16x32_bf16 v[118:121], v[166:169], v[182:185], v[118:121]
	v_mfma_f32_16x16x32_bf16 v[114:117], v[174:177], v[182:185], v[114:117]
	v_mfma_f32_16x16x32_bf16 v[102:105], v[166:169], v[190:193], v[102:105]
	v_mfma_f32_16x16x32_bf16 v[98:101], v[174:177], v[190:193], v[98:101]
	v_mfma_f32_16x16x32_bf16 v[86:89], v[166:169], v[208:211], v[86:89]
	v_mfma_f32_16x16x32_bf16 v[82:85], v[174:177], v[208:211], v[82:85]
	v_mfma_f32_16x16x32_bf16 v[70:73], v[166:169], v[216:219], v[70:73]
	v_mfma_f32_16x16x32_bf16 v[66:69], v[174:177], v[216:219], v[66:69]
	s_barrier
	s_setprio 0
	s_add_i32 s42, s42, s12
	s_mov_b32 m0, s42
	ds_read_b128 v[178:181], v145 offset:16384
	ds_read_b128 v[182:185], v145 offset:17408
	ds_read_b128 v[186:189], v145 offset:18432
	ds_read_b128 v[190:193], v145 offset:19456
	ds_read_b128 v[204:207], v145 offset:20480
	ds_read_b128 v[208:211], v145 offset:21504
	ds_read_b128 v[212:215], v145 offset:22528
	ds_read_b128 v[216:219], v145 offset:23552
	global_load_lds_dwordx4 v0, s[20:21]
	s_add_i32 m0, s42, 0x2000
	s_add_u32 s42, s20, 0x40000
	s_addc_u32 s43, s21, 0
	s_add_i32 s44, s44, s12
	global_load_lds_dwordx4 v130, s[20:21]
	s_mov_b32 m0, s44
	s_nop 0
	global_load_lds_dwordx4 v0, s[42:43]
	s_add_i32 m0, s44, 0x2000
	s_nop 0
	global_load_lds_dwordx4 v130, s[42:43]
	s_mov_b32 m0, s23
	s_nop 0
	global_load_lds_dwordx4 v134, s[60:61]
	s_mov_b32 m0, s24
	s_nop 0
	global_load_lds_dwordx4 v132, s[60:61]
	s_waitcnt vmcnt(8)
	s_waitcnt lgkmcnt(0)
	s_barrier
	s_setprio 1
	v_mfma_f32_16x16x32_bf16 v[62:65], v[146:149], v[178:181], v[62:65]
	v_mfma_f32_16x16x32_bf16 v[58:61], v[154:157], v[178:181], v[58:61]
	v_mfma_f32_16x16x32_bf16 v[46:49], v[146:149], v[186:189], v[46:49]
	v_mfma_f32_16x16x32_bf16 v[42:45], v[154:157], v[186:189], v[42:45]
	v_mfma_f32_16x16x32_bf16 v[30:33], v[146:149], v[204:207], v[30:33]
	v_mfma_f32_16x16x32_bf16 v[26:29], v[154:157], v[204:207], v[26:29]
	v_mfma_f32_16x16x32_bf16 v[14:17], v[146:149], v[212:215], v[14:17]
	v_mfma_f32_16x16x32_bf16 v[10:13], v[154:157], v[212:215], v[10:13]
	v_mfma_f32_16x16x32_bf16 v[62:65], v[150:153], v[182:185], v[62:65]
	v_mfma_f32_16x16x32_bf16 v[58:61], v[158:161], v[182:185], v[58:61]
	v_mfma_f32_16x16x32_bf16 v[46:49], v[150:153], v[190:193], v[46:49]
	v_mfma_f32_16x16x32_bf16 v[42:45], v[158:161], v[190:193], v[42:45]
	v_mfma_f32_16x16x32_bf16 v[30:33], v[150:153], v[208:211], v[30:33]
	v_mfma_f32_16x16x32_bf16 v[26:29], v[158:161], v[208:211], v[26:29]
	v_mfma_f32_16x16x32_bf16 v[14:17], v[150:153], v[216:219], v[14:17]
	v_mfma_f32_16x16x32_bf16 v[10:13], v[158:161], v[216:219], v[10:13]
	s_setprio 0
	s_setprio 1
	v_mfma_f32_16x16x32_bf16 v[54:57], v[162:165], v[178:181], v[54:57]
	v_mfma_f32_16x16x32_bf16 v[50:53], v[170:173], v[178:181], v[50:53]
	v_mfma_f32_16x16x32_bf16 v[38:41], v[162:165], v[186:189], v[38:41]
	v_mfma_f32_16x16x32_bf16 v[34:37], v[170:173], v[186:189], v[34:37]
	v_mfma_f32_16x16x32_bf16 v[22:25], v[162:165], v[204:207], v[22:25]
	v_mfma_f32_16x16x32_bf16 v[18:21], v[170:173], v[204:207], v[18:21]
	v_mfma_f32_16x16x32_bf16 v[6:9], v[162:165], v[212:215], v[6:9]
	v_mfma_f32_16x16x32_bf16 v[2:5], v[170:173], v[212:215], v[2:5]
	v_mfma_f32_16x16x32_bf16 v[54:57], v[166:169], v[182:185], v[54:57]
	v_mfma_f32_16x16x32_bf16 v[50:53], v[174:177], v[182:185], v[50:53]
	v_mfma_f32_16x16x32_bf16 v[38:41], v[166:169], v[190:193], v[38:41]
	v_mfma_f32_16x16x32_bf16 v[34:37], v[174:177], v[190:193], v[34:37]
	v_mfma_f32_16x16x32_bf16 v[22:25], v[166:169], v[208:211], v[22:25]
	v_mfma_f32_16x16x32_bf16 v[18:21], v[174:177], v[208:211], v[18:21]
	v_mfma_f32_16x16x32_bf16 v[6:9], v[166:169], v[216:219], v[6:9]
	v_mfma_f32_16x16x32_bf16 v[2:5], v[174:177], v[216:219], v[2:5]
	s_barrier
; #define PG8_STAGE(bufoff, gbase, voff) do { _Pragma("unroll") for (int _i = 0; _i < 2; ++_i) \
;         __builtin_amdgcn_global_load_lds((const gunsigned*)((const gchar*)(gbase) + (voff)[_i]), (LAS unsigned*)(lds + (bufoff) + ldsw + _i * 8192), 16, 0, 0); } while (0)
; #define PG8_LDA(dst, b, h) do { _Pragma("unroll") for (int m = 0; m < 4; ++m) _Pragma("unroll") for (int k = 0; k < 2; ++k) dst[m][k] = *(const LAS bf16x8*)(lds + PG8_SA(b, h) + aoff + m * 2048 + k * 1024); } while (0)
; #define PG8_LDB(dst, b, h) do { _Pragma("unroll") for (int n = 0; n < 2; ++n) _Pragma("unroll") for (int k = 0; k < 2; ++k) dst[n][k] = *(const LAS bf16x8*)(lds + PG8_SB(b, h) + boff + n * 2048 + k * 1024); } while (0)
; #define PG8_MMA(ai, bj, At, Bt) do { __builtin_amdgcn_s_setprio(1); _Pragma("unroll") for (int m = 0; m < 4; ++m) _Pragma("unroll") for (int n = 0; n < 2; ++n) _Pragma("unroll") for (int k = 0; k < 2; ++k) \
;         acc[ai][bj][m][n] = __builtin_amdgcn_mfma_f32_16x16x32_bf16(Bt[n][k], At[m][k], acc[ai][bj][m][n], 0, 0, 0); __builtin_amdgcn_s_setprio(0); } while (0)
; #define PG8_WAIT_V(n) asm volatile("s_waitcnt vmcnt(" #n ")" ::: "memory")
; #define PG8_WAIT_L(n) asm volatile("s_waitcnt lgkmcnt(" #n ")" ::: "memory")
; #define PG8_BAR __builtin_amdgcn_s_barrier()
; #define PG8_SCHED __builtin_amdgcn_sched_barrier(0)
; template <class Epi, class Sched>
; __device__ __forceinline__ void gemm_phase(LAS unsigned char* lds, const int tid, const Gemm g, const Sched& S, const Epi& E) {
;     ...
;             const bool last = (t == nt - 2);
;             const gchar* a1 = cA + (size_t)(t + 1) * kstep;
;             const gchar* a2 = last ? nA : cA + (size_t)(t + 2) * kstep; const gchar* b2 = last ? nB : cB + (size_t)(t + 2) * kstep;
;             const gchar* a3 = a2 + kstep; const gchar* b3 = b2 + kstep;
;     ...
;             PG8_LDB(B0, 1, 0); PG8_LDB(B1, 1, 1); PG8_SCHED; PG8_LDA(At, 1, 0); PG8_STAGE(PG8_SA(0, 1), a2 + hstep, voffA);
;             PG8_WAIT_V(8); PG8_WAIT_L(0); PG8_BAR; PG8_MMA(0, 0, At, B0); PG8_MMA(0, 1, At, B1); PG8_BAR; PG8_SCHED;
;             PG8_LDA(At, 1, 1); PG8_STAGE(PG8_SB(1, 0), b3, voffB); PG8_STAGE(PG8_SB(1, 1), b3 + hstep, voffB); PG8_STAGE(PG8_SA(1, 0), a3, voffA);
;             PG8_WAIT_V(8); PG8_WAIT_L(0); PG8_BAR; PG8_MMA(1, 0, At, B0); PG8_MMA(1, 1, At, B1); PG8_BAR; PG8_SCHED;
	s_setprio 0
	s_add_i32 s44, 0, 0x18000
	s_add_i32 s45, 0, 0x1c000
	v_add_u32_e32 v158, s44, v143
	v_add_u32_e32 v174, s45, v143
	ds_read_b128 v[146:149], v158
	ds_read_b128 v[150:153], v158 offset:1024
	ds_read_b128 v[154:157], v158 offset:2048
	ds_read_b128 v[158:161], v158 offset:3072
	ds_read_b128 v[162:165], v174
	ds_read_b128 v[166:169], v174 offset:1024
	ds_read_b128 v[170:173], v174 offset:2048
	ds_read_b128 v[174:177], v174 offset:3072
	s_add_u32 s42, s60, 0x40000
	s_addc_u32 s43, s61, 0
	s_mov_b32 m0, s29
	ds_read_b128 v[178:181], v145 offset:32768
	ds_read_b128 v[182:185], v145 offset:33792
	ds_read_b128 v[186:189], v145 offset:34816
	ds_read_b128 v[190:193], v145 offset:35840
	ds_read_b128 v[204:207], v145 offset:36864
	ds_read_b128 v[208:211], v145 offset:37888
	ds_read_b128 v[212:215], v145 offset:38912
	ds_read_b128 v[216:219], v145 offset:39936
	global_load_lds_dwordx4 v134, s[42:43]
	s_mov_b32 m0, s30
	s_nop 0
	global_load_lds_dwordx4 v132, s[42:43]
	s_waitcnt vmcnt(8)
	s_waitcnt lgkmcnt(0)
	s_barrier
	s_setprio 1
	v_mfma_f32_16x16x32_bf16 v[126:129], v[146:149], v[178:181], v[126:129]
	v_mfma_f32_16x16x32_bf16 v[122:125], v[154:157], v[178:181], v[122:125]
	v_mfma_f32_16x16x32_bf16 v[110:113], v[146:149], v[186:189], v[110:113]
	v_mfma_f32_16x16x32_bf16 v[106:109], v[154:157], v[186:189], v[106:109]
	v_mfma_f32_16x16x32_bf16 v[94:97], v[146:149], v[204:207], v[94:97]
	v_mfma_f32_16x16x32_bf16 v[90:93], v[154:157], v[204:207], v[90:93]
	v_mfma_f32_16x16x32_bf16 v[78:81], v[146:149], v[212:215], v[78:81]
	v_mfma_f32_16x16x32_bf16 v[74:77], v[154:157], v[212:215], v[74:77]
	v_mfma_f32_16x16x32_bf16 v[126:129], v[150:153], v[182:185], v[126:129]
	v_mfma_f32_16x16x32_bf16 v[122:125], v[158:161], v[182:185], v[122:125]
	v_mfma_f32_16x16x32_bf16 v[110:113], v[150:153], v[190:193], v[110:113]
	v_mfma_f32_16x16x32_bf16 v[106:109], v[158:161], v[190:193], v[106:109]
	v_mfma_f32_16x16x32_bf16 v[94:97], v[150:153], v[208:211], v[94:97]
	v_mfma_f32_16x16x32_bf16 v[90:93], v[158:161], v[208:211], v[90:93]
	v_mfma_f32_16x16x32_bf16 v[78:81], v[150:153], v[216:219], v[78:81]
	v_mfma_f32_16x16x32_bf16 v[74:77], v[158:161], v[216:219], v[74:77]
	s_setprio 0
	s_setprio 1
	v_mfma_f32_16x16x32_bf16 v[118:121], v[162:165], v[178:181], v[118:121]
	v_mfma_f32_16x16x32_bf16 v[114:117], v[170:173], v[178:181], v[114:117]
	v_mfma_f32_16x16x32_bf16 v[102:105], v[162:165], v[186:189], v[102:105]
	v_mfma_f32_16x16x32_bf16 v[98:101], v[170:173], v[186:189], v[98:101]
	v_mfma_f32_16x16x32_bf16 v[86:89], v[162:165], v[204:207], v[86:89]
	v_mfma_f32_16x16x32_bf16 v[82:85], v[170:173], v[204:207], v[82:85]
	v_mfma_f32_16x16x32_bf16 v[70:73], v[162:165], v[212:215], v[70:73]
	v_mfma_f32_16x16x32_bf16 v[66:69], v[170:173], v[212:215], v[66:69]
	v_mfma_f32_16x16x32_bf16 v[118:121], v[166:169], v[182:185], v[118:121]
	v_mfma_f32_16x16x32_bf16 v[114:117], v[174:177], v[182:185], v[114:117]
	v_mfma_f32_16x16x32_bf16 v[102:105], v[166:169], v[190:193], v[102:105]
	v_mfma_f32_16x16x32_bf16 v[98:101], v[174:177], v[190:193], v[98:101]
	v_mfma_f32_16x16x32_bf16 v[86:89], v[166:169], v[208:211], v[86:89]
	v_mfma_f32_16x16x32_bf16 v[82:85], v[174:177], v[208:211], v[82:85]
	v_mfma_f32_16x16x32_bf16 v[70:73], v[166:169], v[216:219], v[70:73]
	v_mfma_f32_16x16x32_bf16 v[66:69], v[174:177], v[216:219], v[66:69]
	s_barrier
	s_setprio 0
	s_add_i32 s42, s44, s12
	s_mov_b32 m0, s42
	ds_read_b128 v[178:181], v145 offset:49152
	ds_read_b128 v[182:185], v145 offset:50176
	ds_read_b128 v[186:189], v145 offset:51200
	ds_read_b128 v[190:193], v145 offset:52224
	ds_read_b128 v[204:207], v145 offset:53248
	ds_read_b128 v[208:211], v145 offset:54272
	ds_read_b128 v[212:215], v145 offset:55296
	ds_read_b128 v[216:219], v145 offset:56320
	global_load_lds_dwordx4 v141, s[20:21]
	s_add_i32 m0, s42, 0x2000
	s_add_i32 s42, s45, s12
	global_load_lds_dwordx4 v195, s[20:21]
	s_add_u32 s20, s20, 0x40080
	s_addc_u32 s21, s21, 0
	s_mov_b32 m0, s42
	s_nop 0
	global_load_lds_dwordx4 v0, s[20:21]
	s_add_i32 m0, s42, 0x2000
	s_nop 0
	global_load_lds_dwordx4 v130, s[20:21]
	s_mov_b32 m0, s31
	s_nop 0
	global_load_lds_dwordx4 v221, s[60:61]
	s_mov_b32 m0, s34
	s_nop 0
	global_load_lds_dwordx4 v223, s[60:61]
	s_waitcnt vmcnt(8)
	s_waitcnt lgkmcnt(0)
	s_barrier
	s_setprio 1
	v_mfma_f32_16x16x32_bf16 v[62:65], v[146:149], v[178:181], v[62:65]
	v_mfma_f32_16x16x32_bf16 v[58:61], v[154:157], v[178:181], v[58:61]
	v_mfma_f32_16x16x32_bf16 v[46:49], v[146:149], v[186:189], v[46:49]
	v_mfma_f32_16x16x32_bf16 v[42:45], v[154:157], v[186:189], v[42:45]
	v_mfma_f32_16x16x32_bf16 v[30:33], v[146:149], v[204:207], v[30:33]
	v_mfma_f32_16x16x32_bf16 v[26:29], v[154:157], v[204:207], v[26:29]
	v_mfma_f32_16x16x32_bf16 v[14:17], v[146:149], v[212:215], v[14:17]
	v_mfma_f32_16x16x32_bf16 v[10:13], v[154:157], v[212:215], v[10:13]
	v_mfma_f32_16x16x32_bf16 v[62:65], v[150:153], v[182:185], v[62:65]
	v_mfma_f32_16x16x32_bf16 v[58:61], v[158:161], v[182:185], v[58:61]
	v_mfma_f32_16x16x32_bf16 v[46:49], v[150:153], v[190:193], v[46:49]
	v_mfma_f32_16x16x32_bf16 v[42:45], v[158:161], v[190:193], v[42:45]
	v_mfma_f32_16x16x32_bf16 v[30:33], v[150:153], v[208:211], v[30:33]
	v_mfma_f32_16x16x32_bf16 v[26:29], v[158:161], v[208:211], v[26:29]
	v_mfma_f32_16x16x32_bf16 v[14:17], v[150:153], v[216:219], v[14:17]
	v_mfma_f32_16x16x32_bf16 v[10:13], v[158:161], v[216:219], v[10:13]
	s_setprio 0
	s_setprio 1
	s_add_i32 s41, s41, 2
	s_add_u32 s39, s39, 0x100
	s_addc_u32 s40, s40, 0
	s_add_u32 s58, s58, 0x100
	s_addc_u32 s59, s59, 0
	s_cmp_gt_u32 s41, 13
	s_cbranch_scc1 .Lrot_skip_647
	s_add_u32 s20, s58, 0xfffc0080
	s_addc_u32 s21, s59, -1
	s_cmp_eq_u32 s41, 12
	s_cselect_b32 s61, s9, s21
	s_cselect_b32 s60, s37, s20
	s_cselect_b32 s21, s7, s40
	s_cselect_b32 s20, s38, s39
.Lrot_skip_647:
	s_cmp_gt_u32 s41, 13
	v_mfma_f32_16x16x32_bf16 v[54:57], v[162:165], v[178:181], v[54:57]
	v_mfma_f32_16x16x32_bf16 v[50:53], v[170:173], v[178:181], v[50:53]
	v_mfma_f32_16x16x32_bf16 v[38:41], v[162:165], v[186:189], v[38:41]
	v_mfma_f32_16x16x32_bf16 v[34:37], v[170:173], v[186:189], v[34:37]
	v_mfma_f32_16x16x32_bf16 v[22:25], v[162:165], v[204:207], v[22:25]
	v_mfma_f32_16x16x32_bf16 v[18:21], v[170:173], v[204:207], v[18:21]
	v_mfma_f32_16x16x32_bf16 v[6:9], v[162:165], v[212:215], v[6:9]
	v_mfma_f32_16x16x32_bf16 v[2:5], v[170:173], v[212:215], v[2:5]
	v_mfma_f32_16x16x32_bf16 v[54:57], v[166:169], v[182:185], v[54:57]
	v_mfma_f32_16x16x32_bf16 v[50:53], v[174:177], v[182:185], v[50:53]
	v_mfma_f32_16x16x32_bf16 v[38:41], v[166:169], v[190:193], v[38:41]
	v_mfma_f32_16x16x32_bf16 v[34:37], v[174:177], v[190:193], v[34:37]
	v_mfma_f32_16x16x32_bf16 v[22:25], v[166:169], v[208:211], v[22:25]
	v_mfma_f32_16x16x32_bf16 v[18:21], v[174:177], v[208:211], v[18:21]
	v_mfma_f32_16x16x32_bf16 v[6:9], v[166:169], v[216:219], v[6:9]
	v_mfma_f32_16x16x32_bf16 v[2:5], v[174:177], v[216:219], v[2:5]
	s_barrier
	s_setprio 0
	s_cbranch_scc0 .Lrot_647
	s_and_b64 vcc, exec, s[4:5]
	s_cbranch_vccz .LBB0_650
	s_barrier
